# norm-residual epilogue step 5: bf16 xn stores widened from 32 dwordx2 (32-B segments) to 16 dwordx4 (64-B segments) via permlane32_swap+permlane16_swap pairs, both copies; on top of v80
# speedup vs baseline: 1.0090x; 1.0039x over previous
; __device__ __forceinline__ unsigned cvt_pk_bf16(float lo, float hi) { unsigned r; asm volatile("v_cvt_pk_bf16_f32 %0, %1, %2" : "=v"(r) : "v"(lo), "v"(hi)); return r; }
;     __device__ __forceinline__ void fused(f32x4 (&acc)[2][2][4][2], const Unit& u, int wr, int wc, int fr, int fq, PG8_LAS unsigned char* lds, int wid, int lane) const {
;     ...
;         f32x4 g2v[2][2];
; #pragma unroll
;         for (int bj = 0; bj < 2; ++bj)
; #pragma unroll
;             for (int n = 0; n < 2; ++n) g2v[bj][n] = *(const f32x4*)(g2 + col0 + bj * HALF + n * 16);
; #pragma unroll
;         for (int ai = 0; ai < 2; ++ai)
; #pragma unroll
;             for (int m = 0; m < 4; ++m) { const int r = ai * HALF + wr * 64 + m * 16 + fr; const f32x2v sr = S[r]; const size_t off = (size_t)(u.pm * BM + r) * 1024 + col0;
; #pragma unroll
;                 for (int bj = 0; bj < 2; ++bj)
; #pragma unroll
;                     for (int n = 0; n < 2; ++n) { const f32x4 bs = *(const f32x4*)(base + off + bj * HALF + n * 16); const f32x4 x1 = bs + acc[ai][bj][m][n] * sr.x * gv[bj][n];
;                         const f32x4 o = x1 * sr.y * g2v[bj][n]; u32x2 w; w.x = cvt_pk_bf16(o[0], o[1]); w.y = cvt_pk_bf16(o[2], o[3]);
;                         if (!dry || x1[0] == 1.2345e38f) { *(f32x4*)(out + off + bj * HALF + n * 16) = x1; *(u32x2*)(xn + off + bj * HALF + n * 16) = w; } }
;                 if (m & 1) asm volatile("" ::: "memory"); }
.LBB0_858:
	s_or_b64 exec, exec, s[6:7]
	v_and_b32_e32 v224, 63, v228
	v_lshrrev_b32_e32 v224, 4, v224
	v_lshlrev_b32_e32 v224, 3, v224
	v_mov_b32_e32 v225, 0
	v_lshl_add_u64 v[148:149], v[34:35], 2, s[28:29]
	s_mov_b64 s[4:5], 0x2000
	s_waitcnt lgkmcnt(0)
	v_lshl_add_u64 v[150:151], v[148:149], 0, s[4:5]
	v_add_co_u32_e32 v148, vcc, 0x2000, v148
	s_waitcnt lgkmcnt(0)
	s_barrier
	s_nop 0
	v_addc_co_u32_e32 v149, vcc, 0, v149, vcc
	global_load_dwordx4 v[160:163], v[148:149], off
	global_load_dwordx4 v[156:159], v[150:151], off offset:64
	global_load_dwordx4 v[152:155], v[150:151], off offset:512
	s_nop 0
	global_load_dwordx4 v[148:151], v[150:151], off offset:576
	v_lshl_add_u32 v33, v237, 3, 0
	global_load_dwordx4 v[208:211], v[164:165], off
	ds_read_b64 v[206:207], v33 offset:16384
	v_lshlrev_b64 v[166:167], 10, v[166:167]
	s_add_u32 s6, s22, 0xe300000
	v_lshl_add_u64 v[166:167], v[166:167], 0, v[34:35]
	s_addc_u32 s7, s23, 0
	s_waitcnt lgkmcnt(0)
	v_pk_mul_f32 v[146:147], v[146:147], v[206:207] op_sel_hi:[1,0]
	v_pk_mul_f32 v[144:145], v[144:145], v[206:207] op_sel_hi:[1,0]
	v_pk_mul_f32 v[140:141], v[140:141], v[206:207] op_sel_hi:[1,0]
	v_pk_mul_f32 v[142:143], v[142:143], v[206:207] op_sel_hi:[1,0]
	v_pk_mul_f32 v[136:137], v[136:137], v[206:207] op_sel_hi:[1,0]
	v_pk_mul_f32 v[138:139], v[138:139], v[206:207] op_sel_hi:[1,0]
	v_pk_mul_f32 v[132:133], v[132:133], v[206:207] op_sel_hi:[1,0]
	v_pk_mul_f32 v[134:135], v[134:135], v[206:207] op_sel_hi:[1,0]
	s_waitcnt vmcnt(0)
	v_pk_fma_f32 v[144:145], v[116:117], v[144:145], v[208:209]
	v_pk_fma_f32 v[146:147], v[118:119], v[146:147], v[210:211]
	v_pk_mul_f32 v[208:209], v[206:207], v[144:145] op_sel:[1,0]
	v_pk_mul_f32 v[210:211], v[206:207], v[146:147] op_sel:[1,0]
	v_pk_mul_f32 v[208:209], v[160:161], v[208:209]
	v_pk_mul_f32 v[210:211], v[162:163], v[210:211]
	v_cvt_pk_bf16_f32 v208, v208, v209
	s_nop 0
	v_cvt_pk_bf16_f32 v209, v210, v211
	v_lshl_add_u64 v[210:211], v[166:167], 2, s[20:21]
	v_lshl_add_u64 v[166:167], v[166:167], 1, s[6:7]
	global_store_dwordx4 v[210:211], v[144:147], off
	v_mov_b32_e32 v220, v208
	v_mov_b32_e32 v221, v209
	global_load_dwordx4 v[144:147], v[164:165], off offset:64
	s_waitcnt vmcnt(0)
	v_pk_fma_f32 v[140:141], v[104:105], v[140:141], v[144:145]
	v_pk_fma_f32 v[142:143], v[106:107], v[142:143], v[146:147]
	v_pk_mul_f32 v[144:145], v[206:207], v[140:141] op_sel:[1,0]
	v_pk_mul_f32 v[146:147], v[206:207], v[142:143] op_sel:[1,0]
	v_pk_mul_f32 v[144:145], v[156:157], v[144:145]
	v_pk_mul_f32 v[146:147], v[158:159], v[146:147]
	v_cvt_pk_bf16_f32 v144, v144, v145
	s_nop 0
	v_cvt_pk_bf16_f32 v145, v146, v147
	global_store_dwordx4 v[210:211], v[140:143], off offset:64
	v_mov_b32_e32 v222, v144
	v_mov_b32_e32 v223, v145
	v_lshl_add_u64 v[226:227], v[166:167], 0, v[224:225]
	s_nop 0
	v_permlane32_swap_b32_e32 v220, v222
	v_permlane32_swap_b32_e32 v221, v223
	s_nop 1
	v_permlane16_swap_b32_e32 v220, v222
	v_permlane16_swap_b32_e32 v221, v223
	global_store_dwordx4 v[226:227], v[220:223], off
	global_load_dwordx4 v[140:143], v[164:165], off offset:512
	s_waitcnt vmcnt(0)
	v_pk_fma_f32 v[136:137], v[100:101], v[136:137], v[140:141]
	v_pk_fma_f32 v[138:139], v[102:103], v[138:139], v[142:143]
	v_pk_mul_f32 v[140:141], v[206:207], v[136:137] op_sel:[1,0]
	v_pk_mul_f32 v[142:143], v[206:207], v[138:139] op_sel:[1,0]
	v_pk_mul_f32 v[140:141], v[152:153], v[140:141]
	v_pk_mul_f32 v[142:143], v[154:155], v[142:143]
	v_cvt_pk_bf16_f32 v140, v140, v141
	s_nop 0
	v_cvt_pk_bf16_f32 v141, v142, v143
	global_store_dwordx4 v[210:211], v[136:139], off offset:512
	v_mov_b32_e32 v220, v140
	v_mov_b32_e32 v221, v141
	global_load_dwordx4 v[136:139], v[164:165], off offset:576
	s_waitcnt vmcnt(0)
	v_pk_fma_f32 v[132:133], v[92:93], v[132:133], v[136:137]
	v_pk_fma_f32 v[134:135], v[94:95], v[134:135], v[138:139]
	v_pk_mul_f32 v[136:137], v[206:207], v[132:133] op_sel:[1,0]
	v_pk_mul_f32 v[138:139], v[206:207], v[134:135] op_sel:[1,0]
	v_pk_mul_f32 v[136:137], v[148:149], v[136:137]
	v_pk_mul_f32 v[138:139], v[150:151], v[138:139]
	v_cvt_pk_bf16_f32 v136, v136, v137
	s_nop 0
	v_cvt_pk_bf16_f32 v137, v138, v139
	global_store_dwordx4 v[210:211], v[132:135], off offset:576
	v_mov_b32_e32 v222, v136
	v_mov_b32_e32 v223, v137
	v_lshl_add_u64 v[226:227], v[166:167], 0, v[224:225]
	s_nop 0
	v_permlane32_swap_b32_e32 v220, v222
	v_permlane32_swap_b32_e32 v221, v223
	s_nop 1
	v_permlane16_swap_b32_e32 v220, v222
	v_permlane16_swap_b32_e32 v221, v223
	global_store_dwordx4 v[226:227], v[220:223], off offset:256
	ds_read_b64 v[136:137], v33 offset:16512
	v_lshlrev_b64 v[132:133], 10, v[170:171]
	v_lshl_add_u64 v[138:139], v[132:133], 0, v[34:35]
	global_load_dwordx4 v[132:135], v[168:169], off
	s_waitcnt lgkmcnt(0)
	v_pk_mul_f32 v[130:131], v[130:131], v[136:137] op_sel_hi:[1,0]
	v_pk_mul_f32 v[128:129], v[128:129], v[136:137] op_sel_hi:[1,0]
	v_pk_mul_f32 v[124:125], v[124:125], v[136:137] op_sel_hi:[1,0]
	v_pk_mul_f32 v[126:127], v[126:127], v[136:137] op_sel_hi:[1,0]
	v_pk_mul_f32 v[120:121], v[120:121], v[136:137] op_sel_hi:[1,0]
	v_pk_mul_f32 v[122:123], v[122:123], v[136:137] op_sel_hi:[1,0]
	v_pk_mul_f32 v[112:113], v[112:113], v[136:137] op_sel_hi:[1,0]
	v_pk_mul_f32 v[114:115], v[114:115], v[136:137] op_sel_hi:[1,0]
	s_waitcnt vmcnt(0)
; __device__ __forceinline__ unsigned cvt_pk_bf16(float lo, float hi) { unsigned r; asm volatile("v_cvt_pk_bf16_f32 %0, %1, %2" : "=v"(r) : "v"(lo), "v"(hi)); return r; }
;     __device__ __forceinline__ void fused(f32x4 (&acc)[2][2][4][2], const Unit& u, int wr, int wc, int fr, int fq, PG8_LAS unsigned char* lds, int wid, int lane) const {
;     ...
;             for (int m = 0; m < 4; ++m) { const int r = ai * HALF + wr * 64 + m * 16 + fr; const f32x2v sr = S[r]; const size_t off = (size_t)(u.pm * BM + r) * 1024 + col0;
; #pragma unroll
;                 for (int bj = 0; bj < 2; ++bj)
; #pragma unroll
;                     for (int n = 0; n < 2; ++n) { const f32x4 bs = *(const f32x4*)(base + off + bj * HALF + n * 16); const f32x4 x1 = bs + acc[ai][bj][m][n] * sr.x * gv[bj][n];
;                         const f32x4 o = x1 * sr.y * g2v[bj][n]; u32x2 w; w.x = cvt_pk_bf16(o[0], o[1]); w.y = cvt_pk_bf16(o[2], o[3]);
;                         if (!dry || x1[0] == 1.2345e38f) { *(f32x4*)(out + off + bj * HALF + n * 16) = x1; *(u32x2*)(xn + off + bj * HALF + n * 16) = w; } }
;                 if (m & 1) asm volatile("" ::: "memory"); }
	v_pk_fma_f32 v[128:129], v[116:117], v[128:129], v[132:133]
	v_pk_fma_f32 v[130:131], v[118:119], v[130:131], v[134:135]
	v_pk_mul_f32 v[132:133], v[136:137], v[128:129] op_sel:[1,0]
	v_pk_mul_f32 v[134:135], v[136:137], v[130:131] op_sel:[1,0]
	v_pk_mul_f32 v[132:133], v[160:161], v[132:133]
	v_pk_mul_f32 v[134:135], v[162:163], v[134:135]
	v_cvt_pk_bf16_f32 v132, v132, v133
	s_nop 0
	v_cvt_pk_bf16_f32 v133, v134, v135
	v_lshl_add_u64 v[134:135], v[138:139], 2, s[20:21]
	v_lshl_add_u64 v[138:139], v[138:139], 1, s[6:7]
	global_store_dwordx4 v[134:135], v[128:131], off
	v_mov_b32_e32 v220, v132
	v_mov_b32_e32 v221, v133
	global_load_dwordx4 v[128:131], v[168:169], off offset:64
	s_waitcnt vmcnt(0)
	v_pk_fma_f32 v[124:125], v[104:105], v[124:125], v[128:129]
	v_pk_fma_f32 v[126:127], v[106:107], v[126:127], v[130:131]
	v_pk_mul_f32 v[128:129], v[136:137], v[124:125] op_sel:[1,0]
	v_pk_mul_f32 v[130:131], v[136:137], v[126:127] op_sel:[1,0]
	v_pk_mul_f32 v[128:129], v[156:157], v[128:129]
	v_pk_mul_f32 v[130:131], v[158:159], v[130:131]
	v_cvt_pk_bf16_f32 v128, v128, v129
	s_nop 0
	v_cvt_pk_bf16_f32 v129, v130, v131
	global_store_dwordx4 v[134:135], v[124:127], off offset:64
	v_mov_b32_e32 v222, v128
	v_mov_b32_e32 v223, v129
	v_lshl_add_u64 v[226:227], v[138:139], 0, v[224:225]
	s_nop 0
	v_permlane32_swap_b32_e32 v220, v222
	v_permlane32_swap_b32_e32 v221, v223
	s_nop 1
	v_permlane16_swap_b32_e32 v220, v222
	v_permlane16_swap_b32_e32 v221, v223
	global_store_dwordx4 v[226:227], v[220:223], off
	global_load_dwordx4 v[124:127], v[168:169], off offset:512
	s_waitcnt vmcnt(0)
	v_pk_fma_f32 v[120:121], v[100:101], v[120:121], v[124:125]
	v_pk_fma_f32 v[122:123], v[102:103], v[122:123], v[126:127]
	v_pk_mul_f32 v[124:125], v[136:137], v[120:121] op_sel:[1,0]
	v_pk_mul_f32 v[126:127], v[136:137], v[122:123] op_sel:[1,0]
	v_pk_mul_f32 v[124:125], v[152:153], v[124:125]
	v_pk_mul_f32 v[126:127], v[154:155], v[126:127]
	v_cvt_pk_bf16_f32 v124, v124, v125
	s_nop 0
	v_cvt_pk_bf16_f32 v125, v126, v127
	global_store_dwordx4 v[134:135], v[120:123], off offset:512
	v_mov_b32_e32 v220, v124
	v_mov_b32_e32 v221, v125
	global_load_dwordx4 v[120:123], v[168:169], off offset:576
	s_waitcnt vmcnt(0)
	v_pk_fma_f32 v[112:113], v[92:93], v[112:113], v[120:121]
	v_pk_fma_f32 v[114:115], v[94:95], v[114:115], v[122:123]
	v_pk_mul_f32 v[120:121], v[136:137], v[112:113] op_sel:[1,0]
	v_pk_mul_f32 v[122:123], v[136:137], v[114:115] op_sel:[1,0]
	v_pk_mul_f32 v[120:121], v[148:149], v[120:121]
	v_pk_mul_f32 v[122:123], v[150:151], v[122:123]
	v_cvt_pk_bf16_f32 v120, v120, v121
	s_nop 0
	v_cvt_pk_bf16_f32 v121, v122, v123
	global_store_dwordx4 v[134:135], v[112:115], off offset:576
	v_mov_b32_e32 v222, v120
	v_mov_b32_e32 v223, v121
	v_lshl_add_u64 v[226:227], v[138:139], 0, v[224:225]
	s_nop 0
	v_permlane32_swap_b32_e32 v220, v222
	v_permlane32_swap_b32_e32 v221, v223
	s_nop 1
	v_permlane16_swap_b32_e32 v220, v222
	v_permlane16_swap_b32_e32 v221, v223
	global_store_dwordx4 v[226:227], v[220:223], off offset:256
	ds_read_b64 v[120:121], v33 offset:16640
	v_lshlrev_b64 v[112:113], 10, v[174:175]
	v_lshl_add_u64 v[122:123], v[112:113], 0, v[34:35]
	global_load_dwordx4 v[112:115], v[172:173], off
	s_waitcnt lgkmcnt(0)
	v_pk_mul_f32 v[110:111], v[110:111], v[120:121] op_sel_hi:[1,0]
	v_pk_mul_f32 v[108:109], v[108:109], v[120:121] op_sel_hi:[1,0]
	v_pk_mul_f32 v[96:97], v[96:97], v[120:121] op_sel_hi:[1,0]
	v_pk_mul_f32 v[98:99], v[98:99], v[120:121] op_sel_hi:[1,0]
	v_pk_mul_f32 v[88:89], v[88:89], v[120:121] op_sel_hi:[1,0]
	v_pk_mul_f32 v[90:91], v[90:91], v[120:121] op_sel_hi:[1,0]
	v_pk_mul_f32 v[84:85], v[84:85], v[120:121] op_sel_hi:[1,0]
	v_pk_mul_f32 v[86:87], v[86:87], v[120:121] op_sel_hi:[1,0]
	s_waitcnt vmcnt(0)
	v_pk_fma_f32 v[108:109], v[116:117], v[108:109], v[112:113]
	v_pk_fma_f32 v[110:111], v[118:119], v[110:111], v[114:115]
	v_pk_mul_f32 v[112:113], v[120:121], v[108:109] op_sel:[1,0]
	v_pk_mul_f32 v[114:115], v[120:121], v[110:111] op_sel:[1,0]
	v_pk_mul_f32 v[112:113], v[160:161], v[112:113]
	v_pk_mul_f32 v[114:115], v[162:163], v[114:115]
	v_cvt_pk_bf16_f32 v112, v112, v113
	s_nop 0
	v_cvt_pk_bf16_f32 v113, v114, v115
	v_lshl_add_u64 v[114:115], v[122:123], 2, s[20:21]
	v_lshl_add_u64 v[122:123], v[122:123], 1, s[6:7]
	global_store_dwordx4 v[114:115], v[108:111], off
	v_mov_b32_e32 v220, v112
	v_mov_b32_e32 v221, v113
	global_load_dwordx4 v[108:111], v[172:173], off offset:64
	s_waitcnt vmcnt(0)
	v_pk_fma_f32 v[96:97], v[104:105], v[96:97], v[108:109]
	v_pk_fma_f32 v[98:99], v[106:107], v[98:99], v[110:111]
	v_pk_mul_f32 v[108:109], v[120:121], v[96:97] op_sel:[1,0]
	v_pk_mul_f32 v[110:111], v[120:121], v[98:99] op_sel:[1,0]
	v_pk_mul_f32 v[108:109], v[156:157], v[108:109]
	v_pk_mul_f32 v[110:111], v[158:159], v[110:111]
	v_cvt_pk_bf16_f32 v108, v108, v109
	s_nop 0
	v_cvt_pk_bf16_f32 v109, v110, v111
	global_store_dwordx4 v[114:115], v[96:99], off offset:64
	v_mov_b32_e32 v222, v108
	v_mov_b32_e32 v223, v109
	v_lshl_add_u64 v[226:227], v[122:123], 0, v[224:225]
	s_nop 0
	v_permlane32_swap_b32_e32 v220, v222
	v_permlane32_swap_b32_e32 v221, v223
	s_nop 1
	v_permlane16_swap_b32_e32 v220, v222
	v_permlane16_swap_b32_e32 v221, v223
	global_store_dwordx4 v[226:227], v[220:223], off
	global_load_dwordx4 v[96:99], v[172:173], off offset:512
	s_waitcnt vmcnt(0)
	v_pk_fma_f32 v[88:89], v[100:101], v[88:89], v[96:97]
	v_pk_fma_f32 v[90:91], v[102:103], v[90:91], v[98:99]
	v_pk_mul_f32 v[96:97], v[120:121], v[88:89] op_sel:[1,0]
	v_pk_mul_f32 v[98:99], v[120:121], v[90:91] op_sel:[1,0]
	v_pk_mul_f32 v[96:97], v[152:153], v[96:97]
	v_pk_mul_f32 v[98:99], v[154:155], v[98:99]
	v_cvt_pk_bf16_f32 v96, v96, v97
	s_nop 0
	v_cvt_pk_bf16_f32 v97, v98, v99
	global_store_dwordx4 v[114:115], v[88:91], off offset:512
	v_mov_b32_e32 v220, v96
	v_mov_b32_e32 v221, v97
	global_load_dwordx4 v[88:91], v[172:173], off offset:576
	s_waitcnt vmcnt(0)
; __device__ __forceinline__ unsigned cvt_pk_bf16(float lo, float hi) { unsigned r; asm volatile("v_cvt_pk_bf16_f32 %0, %1, %2" : "=v"(r) : "v"(lo), "v"(hi)); return r; }
;     __device__ __forceinline__ void fused(f32x4 (&acc)[2][2][4][2], const Unit& u, int wr, int wc, int fr, int fq, PG8_LAS unsigned char* lds, int wid, int lane) const {
;     ...
;             for (int m = 0; m < 4; ++m) { const int r = ai * HALF + wr * 64 + m * 16 + fr; const f32x2v sr = S[r]; const size_t off = (size_t)(u.pm * BM + r) * 1024 + col0;
; #pragma unroll
;                 for (int bj = 0; bj < 2; ++bj)
; #pragma unroll
;                     for (int n = 0; n < 2; ++n) { const f32x4 bs = *(const f32x4*)(base + off + bj * HALF + n * 16); const f32x4 x1 = bs + acc[ai][bj][m][n] * sr.x * gv[bj][n];
;                         const f32x4 o = x1 * sr.y * g2v[bj][n]; u32x2 w; w.x = cvt_pk_bf16(o[0], o[1]); w.y = cvt_pk_bf16(o[2], o[3]);
;                         if (!dry || x1[0] == 1.2345e38f) { *(f32x4*)(out + off + bj * HALF + n * 16) = x1; *(u32x2*)(xn + off + bj * HALF + n * 16) = w; } }
;                 if (m & 1) asm volatile("" ::: "memory"); }
	v_pk_fma_f32 v[84:85], v[92:93], v[84:85], v[88:89]
	v_pk_fma_f32 v[86:87], v[94:95], v[86:87], v[90:91]
	v_pk_mul_f32 v[88:89], v[120:121], v[84:85] op_sel:[1,0]
	v_pk_mul_f32 v[90:91], v[120:121], v[86:87] op_sel:[1,0]
	v_pk_mul_f32 v[88:89], v[148:149], v[88:89]
	v_pk_mul_f32 v[90:91], v[150:151], v[90:91]
	v_cvt_pk_bf16_f32 v88, v88, v89
	s_nop 0
	v_cvt_pk_bf16_f32 v89, v90, v91
	global_store_dwordx4 v[114:115], v[84:87], off offset:576
	v_mov_b32_e32 v222, v88
	v_mov_b32_e32 v223, v89
	v_lshl_add_u64 v[226:227], v[122:123], 0, v[224:225]
	s_nop 0
	v_permlane32_swap_b32_e32 v220, v222
	v_permlane32_swap_b32_e32 v221, v223
	s_nop 1
	v_permlane16_swap_b32_e32 v220, v222
	v_permlane16_swap_b32_e32 v221, v223
	global_store_dwordx4 v[226:227], v[220:223], off offset:256
	ds_read_b64 v[88:89], v33 offset:16768
	v_lshlrev_b64 v[84:85], 10, v[178:179]
	v_lshl_add_u64 v[90:91], v[84:85], 0, v[34:35]
	global_load_dwordx4 v[84:87], v[176:177], off
	s_waitcnt lgkmcnt(0)
	v_pk_mul_f32 v[82:83], v[82:83], v[88:89] op_sel_hi:[1,0]
	v_pk_mul_f32 v[80:81], v[80:81], v[88:89] op_sel_hi:[1,0]
	v_pk_mul_f32 v[76:77], v[76:77], v[88:89] op_sel_hi:[1,0]
	v_pk_mul_f32 v[78:79], v[78:79], v[88:89] op_sel_hi:[1,0]
	v_pk_mul_f32 v[72:73], v[72:73], v[88:89] op_sel_hi:[1,0]
	v_pk_mul_f32 v[74:75], v[74:75], v[88:89] op_sel_hi:[1,0]
	v_pk_mul_f32 v[68:69], v[68:69], v[88:89] op_sel_hi:[1,0]
	v_pk_mul_f32 v[70:71], v[70:71], v[88:89] op_sel_hi:[1,0]
	s_waitcnt vmcnt(0)
	v_pk_fma_f32 v[80:81], v[116:117], v[80:81], v[84:85]
	v_pk_fma_f32 v[82:83], v[118:119], v[82:83], v[86:87]
	v_pk_mul_f32 v[84:85], v[88:89], v[80:81] op_sel:[1,0]
	v_pk_mul_f32 v[86:87], v[88:89], v[82:83] op_sel:[1,0]
	v_pk_mul_f32 v[84:85], v[160:161], v[84:85]
	v_pk_mul_f32 v[86:87], v[162:163], v[86:87]
	v_cvt_pk_bf16_f32 v84, v84, v85
	s_nop 0
	v_cvt_pk_bf16_f32 v85, v86, v87
	v_lshl_add_u64 v[86:87], v[90:91], 2, s[20:21]
	v_lshl_add_u64 v[90:91], v[90:91], 1, s[6:7]
	global_store_dwordx4 v[86:87], v[80:83], off
	v_mov_b32_e32 v220, v84
	v_mov_b32_e32 v221, v85
	global_load_dwordx4 v[80:83], v[176:177], off offset:64
	s_waitcnt vmcnt(0)
	v_pk_fma_f32 v[76:77], v[104:105], v[76:77], v[80:81]
	v_pk_fma_f32 v[78:79], v[106:107], v[78:79], v[82:83]
	v_pk_mul_f32 v[80:81], v[88:89], v[76:77] op_sel:[1,0]
	v_pk_mul_f32 v[82:83], v[88:89], v[78:79] op_sel:[1,0]
	v_pk_mul_f32 v[80:81], v[156:157], v[80:81]
	v_pk_mul_f32 v[82:83], v[158:159], v[82:83]
	v_cvt_pk_bf16_f32 v80, v80, v81
	s_nop 0
	v_cvt_pk_bf16_f32 v81, v82, v83
	global_store_dwordx4 v[86:87], v[76:79], off offset:64
	v_mov_b32_e32 v222, v80
	v_mov_b32_e32 v223, v81
	v_lshl_add_u64 v[226:227], v[90:91], 0, v[224:225]
	s_nop 0
	v_permlane32_swap_b32_e32 v220, v222
	v_permlane32_swap_b32_e32 v221, v223
	s_nop 1
	v_permlane16_swap_b32_e32 v220, v222
	v_permlane16_swap_b32_e32 v221, v223
	global_store_dwordx4 v[226:227], v[220:223], off
	global_load_dwordx4 v[76:79], v[176:177], off offset:512
	s_waitcnt vmcnt(0)
	v_pk_fma_f32 v[72:73], v[100:101], v[72:73], v[76:77]
	v_pk_fma_f32 v[74:75], v[102:103], v[74:75], v[78:79]
	v_pk_mul_f32 v[76:77], v[88:89], v[72:73] op_sel:[1,0]
	v_pk_mul_f32 v[78:79], v[88:89], v[74:75] op_sel:[1,0]
	v_pk_mul_f32 v[76:77], v[152:153], v[76:77]
	v_pk_mul_f32 v[78:79], v[154:155], v[78:79]
	v_cvt_pk_bf16_f32 v76, v76, v77
	s_nop 0
	v_cvt_pk_bf16_f32 v77, v78, v79
	global_store_dwordx4 v[86:87], v[72:75], off offset:512
	v_mov_b32_e32 v220, v76
	v_mov_b32_e32 v221, v77
	global_load_dwordx4 v[72:75], v[176:177], off offset:576
	s_waitcnt vmcnt(0)
	v_pk_fma_f32 v[68:69], v[92:93], v[68:69], v[72:73]
	v_pk_fma_f32 v[70:71], v[94:95], v[70:71], v[74:75]
	v_pk_mul_f32 v[72:73], v[88:89], v[68:69] op_sel:[1,0]
	v_pk_mul_f32 v[74:75], v[88:89], v[70:71] op_sel:[1,0]
	v_pk_mul_f32 v[72:73], v[148:149], v[72:73]
	v_pk_mul_f32 v[74:75], v[150:151], v[74:75]
	v_cvt_pk_bf16_f32 v72, v72, v73
	s_nop 0
	v_cvt_pk_bf16_f32 v73, v74, v75
	global_store_dwordx4 v[86:87], v[68:71], off offset:576
	v_mov_b32_e32 v222, v72
	v_mov_b32_e32 v223, v73
	v_lshl_add_u64 v[226:227], v[90:91], 0, v[224:225]
	s_nop 0
	v_permlane32_swap_b32_e32 v220, v222
	v_permlane32_swap_b32_e32 v221, v223
	s_nop 1
	v_permlane16_swap_b32_e32 v220, v222
	v_permlane16_swap_b32_e32 v221, v223
	global_store_dwordx4 v[226:227], v[220:223], off offset:256
	ds_read_b64 v[72:73], v33 offset:17408
	v_lshlrev_b64 v[68:69], 10, v[182:183]
	v_lshl_add_u64 v[74:75], v[68:69], 0, v[34:35]
	global_load_dwordx4 v[68:71], v[180:181], off
	s_waitcnt lgkmcnt(0)
	v_pk_mul_f32 v[66:67], v[66:67], v[72:73] op_sel_hi:[1,0]
	v_pk_mul_f32 v[64:65], v[64:65], v[72:73] op_sel_hi:[1,0]
	v_pk_mul_f32 v[60:61], v[60:61], v[72:73] op_sel_hi:[1,0]
	v_pk_mul_f32 v[62:63], v[62:63], v[72:73] op_sel_hi:[1,0]
	v_pk_mul_f32 v[56:57], v[56:57], v[72:73] op_sel_hi:[1,0]
	v_pk_mul_f32 v[58:59], v[58:59], v[72:73] op_sel_hi:[1,0]
	v_pk_mul_f32 v[52:53], v[52:53], v[72:73] op_sel_hi:[1,0]
	v_pk_mul_f32 v[54:55], v[54:55], v[72:73] op_sel_hi:[1,0]
	s_waitcnt vmcnt(0)
	v_pk_fma_f32 v[64:65], v[116:117], v[64:65], v[68:69]
	v_pk_fma_f32 v[66:67], v[118:119], v[66:67], v[70:71]
	v_pk_mul_f32 v[68:69], v[72:73], v[64:65] op_sel:[1,0]
	v_pk_mul_f32 v[70:71], v[72:73], v[66:67] op_sel:[1,0]
	v_pk_mul_f32 v[68:69], v[160:161], v[68:69]
	v_pk_mul_f32 v[70:71], v[162:163], v[70:71]
	v_cvt_pk_bf16_f32 v68, v68, v69
	s_nop 0
	v_cvt_pk_bf16_f32 v69, v70, v71
	v_lshl_add_u64 v[70:71], v[74:75], 2, s[20:21]
	v_lshl_add_u64 v[74:75], v[74:75], 1, s[6:7]
	global_store_dwordx4 v[70:71], v[64:67], off
	v_mov_b32_e32 v220, v68
	v_mov_b32_e32 v221, v69
	global_load_dwordx4 v[64:67], v[180:181], off offset:64
	s_waitcnt vmcnt(0)
; __device__ __forceinline__ unsigned cvt_pk_bf16(float lo, float hi) { unsigned r; asm volatile("v_cvt_pk_bf16_f32 %0, %1, %2" : "=v"(r) : "v"(lo), "v"(hi)); return r; }
;     __device__ __forceinline__ void fused(f32x4 (&acc)[2][2][4][2], const Unit& u, int wr, int wc, int fr, int fq, PG8_LAS unsigned char* lds, int wid, int lane) const {
;     ...
;             for (int m = 0; m < 4; ++m) { const int r = ai * HALF + wr * 64 + m * 16 + fr; const f32x2v sr = S[r]; const size_t off = (size_t)(u.pm * BM + r) * 1024 + col0;
; #pragma unroll
;                 for (int bj = 0; bj < 2; ++bj)
; #pragma unroll
;                     for (int n = 0; n < 2; ++n) { const f32x4 bs = *(const f32x4*)(base + off + bj * HALF + n * 16); const f32x4 x1 = bs + acc[ai][bj][m][n] * sr.x * gv[bj][n];
;                         const f32x4 o = x1 * sr.y * g2v[bj][n]; u32x2 w; w.x = cvt_pk_bf16(o[0], o[1]); w.y = cvt_pk_bf16(o[2], o[3]);
;                         if (!dry || x1[0] == 1.2345e38f) { *(f32x4*)(out + off + bj * HALF + n * 16) = x1; *(u32x2*)(xn + off + bj * HALF + n * 16) = w; } }
;                 if (m & 1) asm volatile("" ::: "memory"); }
	v_pk_fma_f32 v[60:61], v[104:105], v[60:61], v[64:65]
	v_pk_fma_f32 v[62:63], v[106:107], v[62:63], v[66:67]
	v_pk_mul_f32 v[64:65], v[72:73], v[60:61] op_sel:[1,0]
	v_pk_mul_f32 v[66:67], v[72:73], v[62:63] op_sel:[1,0]
	v_pk_mul_f32 v[64:65], v[156:157], v[64:65]
	v_pk_mul_f32 v[66:67], v[158:159], v[66:67]
	v_cvt_pk_bf16_f32 v64, v64, v65
	s_nop 0
	v_cvt_pk_bf16_f32 v65, v66, v67
	global_store_dwordx4 v[70:71], v[60:63], off offset:64
	v_mov_b32_e32 v222, v64
	v_mov_b32_e32 v223, v65
	v_lshl_add_u64 v[226:227], v[74:75], 0, v[224:225]
	s_nop 0
	v_permlane32_swap_b32_e32 v220, v222
	v_permlane32_swap_b32_e32 v221, v223
	s_nop 1
	v_permlane16_swap_b32_e32 v220, v222
	v_permlane16_swap_b32_e32 v221, v223
	global_store_dwordx4 v[226:227], v[220:223], off
	global_load_dwordx4 v[60:63], v[180:181], off offset:512
	s_waitcnt vmcnt(0)
	v_pk_fma_f32 v[56:57], v[100:101], v[56:57], v[60:61]
	v_pk_fma_f32 v[58:59], v[102:103], v[58:59], v[62:63]
	v_pk_mul_f32 v[60:61], v[72:73], v[56:57] op_sel:[1,0]
	v_pk_mul_f32 v[62:63], v[72:73], v[58:59] op_sel:[1,0]
	v_pk_mul_f32 v[60:61], v[152:153], v[60:61]
	v_pk_mul_f32 v[62:63], v[154:155], v[62:63]
	v_cvt_pk_bf16_f32 v60, v60, v61
	s_nop 0
	v_cvt_pk_bf16_f32 v61, v62, v63
	global_store_dwordx4 v[70:71], v[56:59], off offset:512
	v_mov_b32_e32 v220, v60
	v_mov_b32_e32 v221, v61
	global_load_dwordx4 v[56:59], v[180:181], off offset:576
	s_waitcnt vmcnt(0)
	v_pk_fma_f32 v[52:53], v[92:93], v[52:53], v[56:57]
	v_pk_fma_f32 v[54:55], v[94:95], v[54:55], v[58:59]
	v_pk_mul_f32 v[56:57], v[72:73], v[52:53] op_sel:[1,0]
	v_pk_mul_f32 v[58:59], v[72:73], v[54:55] op_sel:[1,0]
	v_pk_mul_f32 v[56:57], v[148:149], v[56:57]
	v_pk_mul_f32 v[58:59], v[150:151], v[58:59]
	v_cvt_pk_bf16_f32 v56, v56, v57
	s_nop 0
	v_cvt_pk_bf16_f32 v57, v58, v59
	global_store_dwordx4 v[70:71], v[52:55], off offset:576
	v_mov_b32_e32 v222, v56
	v_mov_b32_e32 v223, v57
	v_lshl_add_u64 v[226:227], v[74:75], 0, v[224:225]
	s_nop 0
	v_permlane32_swap_b32_e32 v220, v222
	v_permlane32_swap_b32_e32 v221, v223
	s_nop 1
	v_permlane16_swap_b32_e32 v220, v222
	v_permlane16_swap_b32_e32 v221, v223
	global_store_dwordx4 v[226:227], v[220:223], off offset:256
	ds_read_b64 v[56:57], v33 offset:17536
	v_lshlrev_b64 v[52:53], 10, v[186:187]
	v_lshl_add_u64 v[58:59], v[52:53], 0, v[34:35]
	global_load_dwordx4 v[52:55], v[184:185], off
	s_waitcnt lgkmcnt(0)
	v_pk_mul_f32 v[50:51], v[50:51], v[56:57] op_sel_hi:[1,0]
	v_pk_mul_f32 v[48:49], v[48:49], v[56:57] op_sel_hi:[1,0]
	v_pk_mul_f32 v[44:45], v[44:45], v[56:57] op_sel_hi:[1,0]
	v_pk_mul_f32 v[46:47], v[46:47], v[56:57] op_sel_hi:[1,0]
	v_pk_mul_f32 v[40:41], v[40:41], v[56:57] op_sel_hi:[1,0]
	v_pk_mul_f32 v[42:43], v[42:43], v[56:57] op_sel_hi:[1,0]
	v_pk_mul_f32 v[36:37], v[36:37], v[56:57] op_sel_hi:[1,0]
	v_pk_mul_f32 v[38:39], v[38:39], v[56:57] op_sel_hi:[1,0]
	s_waitcnt vmcnt(0)
	v_pk_fma_f32 v[48:49], v[116:117], v[48:49], v[52:53]
	v_pk_fma_f32 v[50:51], v[118:119], v[50:51], v[54:55]
	v_pk_mul_f32 v[52:53], v[56:57], v[48:49] op_sel:[1,0]
	v_pk_mul_f32 v[54:55], v[56:57], v[50:51] op_sel:[1,0]
	v_pk_mul_f32 v[52:53], v[160:161], v[52:53]
	v_pk_mul_f32 v[54:55], v[162:163], v[54:55]
	v_cvt_pk_bf16_f32 v52, v52, v53
	s_nop 0
	v_cvt_pk_bf16_f32 v53, v54, v55
	v_lshl_add_u64 v[54:55], v[58:59], 2, s[20:21]
	v_lshl_add_u64 v[58:59], v[58:59], 1, s[6:7]
	global_store_dwordx4 v[54:55], v[48:51], off
	v_mov_b32_e32 v220, v52
	v_mov_b32_e32 v221, v53
	global_load_dwordx4 v[48:51], v[184:185], off offset:64
	s_waitcnt vmcnt(0)
	v_pk_fma_f32 v[44:45], v[104:105], v[44:45], v[48:49]
	v_pk_fma_f32 v[46:47], v[106:107], v[46:47], v[50:51]
	v_pk_mul_f32 v[48:49], v[56:57], v[44:45] op_sel:[1,0]
	v_pk_mul_f32 v[50:51], v[56:57], v[46:47] op_sel:[1,0]
	v_pk_mul_f32 v[48:49], v[156:157], v[48:49]
	v_pk_mul_f32 v[50:51], v[158:159], v[50:51]
	v_cvt_pk_bf16_f32 v48, v48, v49
	s_nop 0
	v_cvt_pk_bf16_f32 v49, v50, v51
	global_store_dwordx4 v[54:55], v[44:47], off offset:64
	v_mov_b32_e32 v222, v48
	v_mov_b32_e32 v223, v49
	v_lshl_add_u64 v[226:227], v[58:59], 0, v[224:225]
	s_nop 0
	v_permlane32_swap_b32_e32 v220, v222
	v_permlane32_swap_b32_e32 v221, v223
	s_nop 1
	v_permlane16_swap_b32_e32 v220, v222
	v_permlane16_swap_b32_e32 v221, v223
	global_store_dwordx4 v[226:227], v[220:223], off
	global_load_dwordx4 v[44:47], v[184:185], off offset:512
	s_waitcnt vmcnt(0)
	v_pk_fma_f32 v[40:41], v[100:101], v[40:41], v[44:45]
	v_pk_fma_f32 v[42:43], v[102:103], v[42:43], v[46:47]
	v_pk_mul_f32 v[44:45], v[56:57], v[40:41] op_sel:[1,0]
	v_pk_mul_f32 v[46:47], v[56:57], v[42:43] op_sel:[1,0]
	v_pk_mul_f32 v[44:45], v[152:153], v[44:45]
	v_pk_mul_f32 v[46:47], v[154:155], v[46:47]
	v_cvt_pk_bf16_f32 v44, v44, v45
	s_nop 0
	v_cvt_pk_bf16_f32 v45, v46, v47
	global_store_dwordx4 v[54:55], v[40:43], off offset:512
	v_mov_b32_e32 v220, v44
	v_mov_b32_e32 v221, v45
	global_load_dwordx4 v[40:43], v[184:185], off offset:576
	s_waitcnt vmcnt(0)
	v_pk_fma_f32 v[36:37], v[92:93], v[36:37], v[40:41]
	v_pk_fma_f32 v[38:39], v[94:95], v[38:39], v[42:43]
	v_pk_mul_f32 v[40:41], v[56:57], v[36:37] op_sel:[1,0]
	v_pk_mul_f32 v[42:43], v[56:57], v[38:39] op_sel:[1,0]
	v_pk_mul_f32 v[40:41], v[148:149], v[40:41]
	v_pk_mul_f32 v[42:43], v[150:151], v[42:43]
	v_cvt_pk_bf16_f32 v40, v40, v41
	s_nop 0
	v_cvt_pk_bf16_f32 v41, v42, v43
	global_store_dwordx4 v[54:55], v[36:39], off offset:576
	v_mov_b32_e32 v222, v40
	v_mov_b32_e32 v223, v41
	v_lshl_add_u64 v[226:227], v[58:59], 0, v[224:225]
	s_nop 0
	v_permlane32_swap_b32_e32 v220, v222
	v_permlane32_swap_b32_e32 v221, v223
	s_nop 1
	v_permlane16_swap_b32_e32 v220, v222
	v_permlane16_swap_b32_e32 v221, v223
	global_store_dwordx4 v[226:227], v[220:223], off offset:256
	ds_read_b64 v[40:41], v33 offset:17664
	v_lshlrev_b64 v[36:37], 10, v[190:191]
	v_lshl_add_u64 v[42:43], v[36:37], 0, v[34:35]
	global_load_dwordx4 v[36:39], v[188:189], off
	s_waitcnt lgkmcnt(0)
; __device__ __forceinline__ unsigned cvt_pk_bf16(float lo, float hi) { unsigned r; asm volatile("v_cvt_pk_bf16_f32 %0, %1, %2" : "=v"(r) : "v"(lo), "v"(hi)); return r; }
;     __device__ __forceinline__ void fused(f32x4 (&acc)[2][2][4][2], const Unit& u, int wr, int wc, int fr, int fq, PG8_LAS unsigned char* lds, int wid, int lane) const {
;     ...
;             for (int m = 0; m < 4; ++m) { const int r = ai * HALF + wr * 64 + m * 16 + fr; const f32x2v sr = S[r]; const size_t off = (size_t)(u.pm * BM + r) * 1024 + col0;
; #pragma unroll
;                 for (int bj = 0; bj < 2; ++bj)
; #pragma unroll
;                     for (int n = 0; n < 2; ++n) { const f32x4 bs = *(const f32x4*)(base + off + bj * HALF + n * 16); const f32x4 x1 = bs + acc[ai][bj][m][n] * sr.x * gv[bj][n];
;                         const f32x4 o = x1 * sr.y * g2v[bj][n]; u32x2 w; w.x = cvt_pk_bf16(o[0], o[1]); w.y = cvt_pk_bf16(o[2], o[3]);
;                         if (!dry || x1[0] == 1.2345e38f) { *(f32x4*)(out + off + bj * HALF + n * 16) = x1; *(u32x2*)(xn + off + bj * HALF + n * 16) = w; } }
;                 if (m & 1) asm volatile("" ::: "memory"); }
	v_pk_mul_f32 v[30:31], v[30:31], v[40:41] op_sel_hi:[1,0]
	v_pk_mul_f32 v[28:29], v[28:29], v[40:41] op_sel_hi:[1,0]
	v_pk_mul_f32 v[24:25], v[24:25], v[40:41] op_sel_hi:[1,0]
	v_pk_mul_f32 v[26:27], v[26:27], v[40:41] op_sel_hi:[1,0]
	v_pk_mul_f32 v[20:21], v[20:21], v[40:41] op_sel_hi:[1,0]
	v_pk_mul_f32 v[22:23], v[22:23], v[40:41] op_sel_hi:[1,0]
	v_pk_mul_f32 v[16:17], v[16:17], v[40:41] op_sel_hi:[1,0]
	v_pk_mul_f32 v[18:19], v[18:19], v[40:41] op_sel_hi:[1,0]
	s_waitcnt vmcnt(0)
	v_pk_fma_f32 v[28:29], v[116:117], v[28:29], v[36:37]
	v_pk_fma_f32 v[30:31], v[118:119], v[30:31], v[38:39]
	v_pk_mul_f32 v[36:37], v[40:41], v[28:29] op_sel:[1,0]
	v_pk_mul_f32 v[38:39], v[40:41], v[30:31] op_sel:[1,0]
	v_pk_mul_f32 v[36:37], v[160:161], v[36:37]
	v_pk_mul_f32 v[38:39], v[162:163], v[38:39]
	v_cvt_pk_bf16_f32 v36, v36, v37
	s_nop 0
	v_cvt_pk_bf16_f32 v37, v38, v39
	v_lshl_add_u64 v[38:39], v[42:43], 2, s[20:21]
	v_lshl_add_u64 v[42:43], v[42:43], 1, s[6:7]
	global_store_dwordx4 v[38:39], v[28:31], off
	v_mov_b32_e32 v220, v36
	v_mov_b32_e32 v221, v37
	global_load_dwordx4 v[28:31], v[188:189], off offset:64
	s_waitcnt vmcnt(0)
	v_pk_fma_f32 v[24:25], v[104:105], v[24:25], v[28:29]
	v_pk_fma_f32 v[26:27], v[106:107], v[26:27], v[30:31]
	v_pk_mul_f32 v[28:29], v[40:41], v[24:25] op_sel:[1,0]
	v_pk_mul_f32 v[30:31], v[40:41], v[26:27] op_sel:[1,0]
	v_pk_mul_f32 v[28:29], v[156:157], v[28:29]
	v_pk_mul_f32 v[30:31], v[158:159], v[30:31]
	v_cvt_pk_bf16_f32 v28, v28, v29
	s_nop 0
	v_cvt_pk_bf16_f32 v29, v30, v31
	global_store_dwordx4 v[38:39], v[24:27], off offset:64
	v_mov_b32_e32 v222, v28
	v_mov_b32_e32 v223, v29
	v_lshl_add_u64 v[226:227], v[42:43], 0, v[224:225]
	s_nop 0
	v_permlane32_swap_b32_e32 v220, v222
	v_permlane32_swap_b32_e32 v221, v223
	s_nop 1
	v_permlane16_swap_b32_e32 v220, v222
	v_permlane16_swap_b32_e32 v221, v223
	global_store_dwordx4 v[226:227], v[220:223], off
	global_load_dwordx4 v[24:27], v[188:189], off offset:512
	s_waitcnt vmcnt(0)
	v_pk_fma_f32 v[20:21], v[100:101], v[20:21], v[24:25]
	v_pk_fma_f32 v[22:23], v[102:103], v[22:23], v[26:27]
	v_pk_mul_f32 v[24:25], v[40:41], v[20:21] op_sel:[1,0]
	v_pk_mul_f32 v[26:27], v[40:41], v[22:23] op_sel:[1,0]
	v_pk_mul_f32 v[24:25], v[152:153], v[24:25]
	v_pk_mul_f32 v[26:27], v[154:155], v[26:27]
	v_cvt_pk_bf16_f32 v24, v24, v25
	s_nop 0
	v_cvt_pk_bf16_f32 v25, v26, v27
	global_store_dwordx4 v[38:39], v[20:23], off offset:512
	v_mov_b32_e32 v220, v24
	v_mov_b32_e32 v221, v25
	global_load_dwordx4 v[20:23], v[188:189], off offset:576
	s_waitcnt vmcnt(0)
	v_pk_fma_f32 v[16:17], v[92:93], v[16:17], v[20:21]
	v_pk_fma_f32 v[18:19], v[94:95], v[18:19], v[22:23]
	v_pk_mul_f32 v[20:21], v[40:41], v[16:17] op_sel:[1,0]
	v_pk_mul_f32 v[22:23], v[40:41], v[18:19] op_sel:[1,0]
	v_pk_mul_f32 v[20:21], v[148:149], v[20:21]
	v_pk_mul_f32 v[22:23], v[150:151], v[22:23]
	v_cvt_pk_bf16_f32 v20, v20, v21
	s_nop 0
	v_cvt_pk_bf16_f32 v21, v22, v23
	global_store_dwordx4 v[38:39], v[16:19], off offset:576
	v_mov_b32_e32 v222, v20
	v_mov_b32_e32 v223, v21
	v_lshl_add_u64 v[226:227], v[42:43], 0, v[224:225]
	s_nop 0
	v_permlane32_swap_b32_e32 v220, v222
	v_permlane32_swap_b32_e32 v221, v223
	s_nop 1
	v_permlane16_swap_b32_e32 v220, v222
	v_permlane16_swap_b32_e32 v221, v223
	global_store_dwordx4 v[226:227], v[220:223], off offset:256
	ds_read_b64 v[20:21], v33 offset:17792
	v_lshlrev_b64 v[16:17], 10, v[204:205]
	v_lshl_add_u64 v[22:23], v[16:17], 0, v[34:35]
	global_load_dwordx4 v[16:19], v[192:193], off
	s_waitcnt lgkmcnt(0)
	v_pk_mul_f32 v[14:15], v[14:15], v[20:21] op_sel_hi:[1,0]
	v_pk_mul_f32 v[12:13], v[12:13], v[20:21] op_sel_hi:[1,0]
	v_pk_mul_f32 v[8:9], v[8:9], v[20:21] op_sel_hi:[1,0]
	v_pk_mul_f32 v[10:11], v[10:11], v[20:21] op_sel_hi:[1,0]
	v_pk_mul_f32 v[4:5], v[4:5], v[20:21] op_sel_hi:[1,0]
	v_pk_mul_f32 v[6:7], v[6:7], v[20:21] op_sel_hi:[1,0]
	v_pk_mul_f32 v[0:1], v[0:1], v[20:21] op_sel_hi:[1,0]
	v_pk_mul_f32 v[2:3], v[2:3], v[20:21] op_sel_hi:[1,0]
	s_waitcnt vmcnt(0)
	v_pk_fma_f32 v[12:13], v[116:117], v[12:13], v[16:17]
	v_pk_fma_f32 v[14:15], v[118:119], v[14:15], v[18:19]
	v_pk_mul_f32 v[16:17], v[20:21], v[12:13] op_sel:[1,0]
	v_pk_mul_f32 v[18:19], v[20:21], v[14:15] op_sel:[1,0]
	v_pk_mul_f32 v[16:17], v[160:161], v[16:17]
	v_pk_mul_f32 v[18:19], v[162:163], v[18:19]
	v_cvt_pk_bf16_f32 v16, v16, v17
	s_nop 0
	v_cvt_pk_bf16_f32 v17, v18, v19
	v_lshl_add_u64 v[18:19], v[22:23], 2, s[20:21]
	v_lshl_add_u64 v[22:23], v[22:23], 1, s[6:7]
	global_store_dwordx4 v[18:19], v[12:15], off
	v_mov_b32_e32 v220, v16
	v_mov_b32_e32 v221, v17
	global_load_dwordx4 v[12:15], v[192:193], off offset:64
	s_waitcnt vmcnt(0)
	v_pk_fma_f32 v[8:9], v[104:105], v[8:9], v[12:13]
	v_pk_fma_f32 v[10:11], v[106:107], v[10:11], v[14:15]
	v_pk_mul_f32 v[12:13], v[20:21], v[8:9] op_sel:[1,0]
	v_pk_mul_f32 v[14:15], v[20:21], v[10:11] op_sel:[1,0]
	v_pk_mul_f32 v[12:13], v[156:157], v[12:13]
	v_pk_mul_f32 v[14:15], v[158:159], v[14:15]
	v_cvt_pk_bf16_f32 v12, v12, v13
	s_nop 0
	v_cvt_pk_bf16_f32 v13, v14, v15
	global_store_dwordx4 v[18:19], v[8:11], off offset:64
	v_mov_b32_e32 v222, v12
	v_mov_b32_e32 v223, v13
	v_lshl_add_u64 v[226:227], v[22:23], 0, v[224:225]
	s_nop 0
	v_permlane32_swap_b32_e32 v220, v222
	v_permlane32_swap_b32_e32 v221, v223
	s_nop 1
	v_permlane16_swap_b32_e32 v220, v222
	v_permlane16_swap_b32_e32 v221, v223
	global_store_dwordx4 v[226:227], v[220:223], off
	global_load_dwordx4 v[8:11], v[192:193], off offset:512
	s_waitcnt vmcnt(0)
	v_pk_fma_f32 v[4:5], v[100:101], v[4:5], v[8:9]
	v_pk_fma_f32 v[6:7], v[102:103], v[6:7], v[10:11]
	v_pk_mul_f32 v[8:9], v[20:21], v[4:5] op_sel:[1,0]
	v_pk_mul_f32 v[10:11], v[20:21], v[6:7] op_sel:[1,0]
	v_pk_mul_f32 v[8:9], v[152:153], v[8:9]
	v_pk_mul_f32 v[10:11], v[154:155], v[10:11]
	v_cvt_pk_bf16_f32 v8, v8, v9
	s_nop 0
	v_cvt_pk_bf16_f32 v9, v10, v11
	global_store_dwordx4 v[18:19], v[4:7], off offset:512
	v_mov_b32_e32 v220, v8
	v_mov_b32_e32 v221, v9
	global_load_dwordx4 v[4:7], v[192:193], off offset:576
	s_waitcnt vmcnt(0)
	v_pk_fma_f32 v[0:1], v[92:93], v[0:1], v[4:5]
	v_pk_fma_f32 v[2:3], v[94:95], v[2:3], v[6:7]
	v_pk_mul_f32 v[4:5], v[20:21], v[0:1] op_sel:[1,0]
	v_pk_mul_f32 v[6:7], v[20:21], v[2:3] op_sel:[1,0]
	v_pk_mul_f32 v[4:5], v[148:149], v[4:5]
	v_pk_mul_f32 v[6:7], v[150:151], v[6:7]
	v_cvt_pk_bf16_f32 v4, v4, v5
	s_nop 0
	v_cvt_pk_bf16_f32 v5, v6, v7
	global_store_dwordx4 v[18:19], v[0:3], off offset:576
	v_mov_b32_e32 v222, v4
	v_mov_b32_e32 v223, v5
	v_lshl_add_u64 v[226:227], v[22:23], 0, v[224:225]
	s_nop 0
	v_permlane32_swap_b32_e32 v220, v222
	v_permlane32_swap_b32_e32 v221, v223
	s_nop 1
	v_permlane16_swap_b32_e32 v220, v222
	v_permlane16_swap_b32_e32 v221, v223
	global_store_dwordx4 v[226:227], v[220:223], off offset:256

; __device__ __forceinline__ unsigned cvt_pk_bf16(float lo, float hi) { unsigned r; asm volatile("v_cvt_pk_bf16_f32 %0, %1, %2" : "=v"(r) : "v"(lo), "v"(hi)); return r; }
;     __device__ __forceinline__ void fused(f32x4 (&acc)[2][2][4][2], const Unit& u, int wr, int wc, int fr, int fq, PG8_LAS unsigned char* lds, int wid, int lane) const {
;     ...
;         f32x4 g2v[2][2];
; #pragma unroll
;         for (int bj = 0; bj < 2; ++bj)
; #pragma unroll
;             for (int n = 0; n < 2; ++n) g2v[bj][n] = *(const f32x4*)(g2 + col0 + bj * HALF + n * 16);
; #pragma unroll
;         for (int ai = 0; ai < 2; ++ai)
; #pragma unroll
;             for (int m = 0; m < 4; ++m) { const int r = ai * HALF + wr * 64 + m * 16 + fr; const f32x2v sr = S[r]; const size_t off = (size_t)(u.pm * BM + r) * 1024 + col0;
; #pragma unroll
;                 for (int bj = 0; bj < 2; ++bj)
; #pragma unroll
;                     for (int n = 0; n < 2; ++n) { const f32x4 bs = *(const f32x4*)(base + off + bj * HALF + n * 16); const f32x4 x1 = bs + acc[ai][bj][m][n] * sr.x * gv[bj][n];
;                         const f32x4 o = x1 * sr.y * g2v[bj][n]; u32x2 w; w.x = cvt_pk_bf16(o[0], o[1]); w.y = cvt_pk_bf16(o[2], o[3]);
;                         if (!dry || x1[0] == 1.2345e38f) { *(f32x4*)(out + off + bj * HALF + n * 16) = x1; *(u32x2*)(xn + off + bj * HALF + n * 16) = w; } }
;                 if (m & 1) asm volatile("" ::: "memory"); }
.LBB0_1115:
	s_or_b64 exec, exec, s[6:7]
	v_and_b32_e32 v224, 63, v228
	v_lshrrev_b32_e32 v224, 4, v224
	v_lshlrev_b32_e32 v224, 3, v224
	v_mov_b32_e32 v225, 0
	s_ashr_i32 s19, s18, 31
	s_lshl_b64 s[4:5], s[18:19], 14
	s_add_u32 s6, s26, s4
	s_addc_u32 s7, s27, s5
	s_and_b64 s[4:5], s[22:23], exec
	s_cselect_b32 s4, s7, s43
	s_cselect_b32 s5, s6, s42
	s_waitcnt lgkmcnt(0)
	s_barrier
	global_load_dwordx4 v[160:163], v[164:165], off
	v_mov_b32_e32 v148, s5
	v_mov_b32_e32 v149, s4
	v_lshl_add_u64 v[206:207], v[34:35], 2, v[148:149]
	global_load_dwordx4 v[152:155], v[206:207], off
	v_lshl_add_u32 v33, v237, 3, 0
	ds_read_b64 v[208:209], v33 offset:16384
	v_lshlrev_b64 v[148:149], 10, v[166:167]
	s_add_u32 s6, s24, 0xe300000
	v_lshl_add_u64 v[148:149], v[148:149], 0, v[34:35]
	s_addc_u32 s7, s25, 0
	s_waitcnt lgkmcnt(0)
	v_pk_mul_f32 v[210:211], v[128:129], v[208:209] op_sel_hi:[1,0]
	v_pk_mul_f32 v[166:167], v[130:131], v[208:209] op_sel_hi:[1,0]
	v_lshl_add_u64 v[212:213], v[148:149], 1, s[6:7]
	global_load_dwordx4 v[156:159], v[206:207], off offset:64
	global_load_dwordx4 v[148:151], v[206:207], off offset:512
	global_load_dwordx4 v[128:131], v[206:207], off offset:576
	v_pk_mul_f32 v[124:125], v[124:125], v[208:209] op_sel_hi:[1,0]
	v_pk_mul_f32 v[126:127], v[126:127], v[208:209] op_sel_hi:[1,0]
	v_pk_mul_f32 v[120:121], v[120:121], v[208:209] op_sel_hi:[1,0]
	v_pk_mul_f32 v[122:123], v[122:123], v[208:209] op_sel_hi:[1,0]
	v_pk_mul_f32 v[116:117], v[116:117], v[208:209] op_sel_hi:[1,0]
	v_pk_mul_f32 v[118:119], v[118:119], v[208:209] op_sel_hi:[1,0]
	s_waitcnt vmcnt(4)
	v_pk_fma_f32 v[160:161], v[144:145], v[210:211], v[160:161]
	v_pk_fma_f32 v[162:163], v[146:147], v[166:167], v[162:163]
	v_pk_mul_f32 v[166:167], v[208:209], v[160:161] op_sel:[1,0]
	v_pk_mul_f32 v[206:207], v[208:209], v[162:163] op_sel:[1,0]
	s_waitcnt vmcnt(3)
	v_pk_mul_f32 v[166:167], v[152:153], v[166:167]
	v_pk_mul_f32 v[206:207], v[154:155], v[206:207]
	v_cvt_pk_bf16_f32 v166, v166, v167
	s_nop 0
	v_cvt_pk_bf16_f32 v167, v206, v207
	global_store_dwordx4 v[164:165], v[160:163], off
	v_mov_b32_e32 v220, v166
	v_mov_b32_e32 v221, v167
	global_load_dwordx4 v[160:163], v[164:165], off offset:64
	s_waitcnt vmcnt(0)
	v_pk_fma_f32 v[124:125], v[140:141], v[124:125], v[160:161]
	v_pk_fma_f32 v[126:127], v[142:143], v[126:127], v[162:163]
	v_pk_mul_f32 v[160:161], v[208:209], v[124:125] op_sel:[1,0]
	v_pk_mul_f32 v[162:163], v[208:209], v[126:127] op_sel:[1,0]
	v_pk_mul_f32 v[160:161], v[156:157], v[160:161]
	v_pk_mul_f32 v[162:163], v[158:159], v[162:163]
	v_cvt_pk_bf16_f32 v160, v160, v161
	s_nop 0
	v_cvt_pk_bf16_f32 v161, v162, v163
	global_store_dwordx4 v[164:165], v[124:127], off offset:64
	v_mov_b32_e32 v222, v160
	v_mov_b32_e32 v223, v161
	v_lshl_add_u64 v[226:227], v[212:213], 0, v[224:225]
	s_nop 0
	v_permlane32_swap_b32_e32 v220, v222
	v_permlane32_swap_b32_e32 v221, v223
	s_nop 1
	v_permlane16_swap_b32_e32 v220, v222
	v_permlane16_swap_b32_e32 v221, v223
	global_store_dwordx4 v[226:227], v[220:223], off
	global_load_dwordx4 v[124:127], v[164:165], off offset:512
	s_waitcnt vmcnt(0)
	v_pk_fma_f32 v[120:121], v[136:137], v[120:121], v[124:125]
	v_pk_fma_f32 v[122:123], v[138:139], v[122:123], v[126:127]
	v_pk_mul_f32 v[124:125], v[208:209], v[120:121] op_sel:[1,0]
	v_pk_mul_f32 v[126:127], v[208:209], v[122:123] op_sel:[1,0]
	v_pk_mul_f32 v[124:125], v[148:149], v[124:125]
	v_pk_mul_f32 v[126:127], v[150:151], v[126:127]
	v_cvt_pk_bf16_f32 v124, v124, v125
	s_nop 0
	v_cvt_pk_bf16_f32 v125, v126, v127
	global_store_dwordx4 v[164:165], v[120:123], off offset:512
	v_mov_b32_e32 v220, v124
	v_mov_b32_e32 v221, v125
	global_load_dwordx4 v[120:123], v[164:165], off offset:576
	s_waitcnt vmcnt(0)
	v_pk_fma_f32 v[116:117], v[132:133], v[116:117], v[120:121]
	v_pk_fma_f32 v[118:119], v[134:135], v[118:119], v[122:123]
	v_pk_mul_f32 v[120:121], v[208:209], v[116:117] op_sel:[1,0]
	v_pk_mul_f32 v[122:123], v[208:209], v[118:119] op_sel:[1,0]
	v_pk_mul_f32 v[120:121], v[128:129], v[120:121]
	v_pk_mul_f32 v[122:123], v[130:131], v[122:123]
	v_cvt_pk_bf16_f32 v120, v120, v121
	s_nop 0
	v_cvt_pk_bf16_f32 v121, v122, v123
	global_store_dwordx4 v[164:165], v[116:119], off offset:576
	v_mov_b32_e32 v222, v120
	v_mov_b32_e32 v223, v121
	v_lshl_add_u64 v[226:227], v[212:213], 0, v[224:225]
	s_nop 0
	v_permlane32_swap_b32_e32 v220, v222
	v_permlane32_swap_b32_e32 v221, v223
	s_nop 1
	v_permlane16_swap_b32_e32 v220, v222
	v_permlane16_swap_b32_e32 v221, v223
	global_store_dwordx4 v[226:227], v[220:223], off offset:256
	global_load_dwordx4 v[116:119], v[168:169], off
	ds_read_b64 v[120:121], v33 offset:16512
	v_lshlrev_b64 v[122:123], 10, v[170:171]
	v_lshl_add_u64 v[122:123], v[122:123], 0, v[34:35]
	v_lshl_add_u64 v[122:123], v[122:123], 1, s[6:7]
	s_waitcnt lgkmcnt(0)
	v_pk_mul_f32 v[112:113], v[112:113], v[120:121] op_sel_hi:[1,0]
	v_pk_mul_f32 v[114:115], v[114:115], v[120:121] op_sel_hi:[1,0]
	v_pk_mul_f32 v[108:109], v[108:109], v[120:121] op_sel_hi:[1,0]
	v_pk_mul_f32 v[110:111], v[110:111], v[120:121] op_sel_hi:[1,0]
	v_pk_mul_f32 v[104:105], v[104:105], v[120:121] op_sel_hi:[1,0]
	v_pk_mul_f32 v[106:107], v[106:107], v[120:121] op_sel_hi:[1,0]
	v_pk_mul_f32 v[100:101], v[100:101], v[120:121] op_sel_hi:[1,0]
	v_pk_mul_f32 v[102:103], v[102:103], v[120:121] op_sel_hi:[1,0]
	s_waitcnt vmcnt(0)
; __device__ __forceinline__ unsigned cvt_pk_bf16(float lo, float hi) { unsigned r; asm volatile("v_cvt_pk_bf16_f32 %0, %1, %2" : "=v"(r) : "v"(lo), "v"(hi)); return r; }
;     __device__ __forceinline__ void fused(f32x4 (&acc)[2][2][4][2], const Unit& u, int wr, int wc, int fr, int fq, PG8_LAS unsigned char* lds, int wid, int lane) const {
;     ...
;             for (int m = 0; m < 4; ++m) { const int r = ai * HALF + wr * 64 + m * 16 + fr; const f32x2v sr = S[r]; const size_t off = (size_t)(u.pm * BM + r) * 1024 + col0;
; #pragma unroll
;                 for (int bj = 0; bj < 2; ++bj)
; #pragma unroll
;                     for (int n = 0; n < 2; ++n) { const f32x4 bs = *(const f32x4*)(base + off + bj * HALF + n * 16); const f32x4 x1 = bs + acc[ai][bj][m][n] * sr.x * gv[bj][n];
;                         const f32x4 o = x1 * sr.y * g2v[bj][n]; u32x2 w; w.x = cvt_pk_bf16(o[0], o[1]); w.y = cvt_pk_bf16(o[2], o[3]);
;                         if (!dry || x1[0] == 1.2345e38f) { *(f32x4*)(out + off + bj * HALF + n * 16) = x1; *(u32x2*)(xn + off + bj * HALF + n * 16) = w; } }
;                 if (m & 1) asm volatile("" ::: "memory"); }
	v_pk_fma_f32 v[112:113], v[144:145], v[112:113], v[116:117]
	v_pk_fma_f32 v[114:115], v[146:147], v[114:115], v[118:119]
	v_pk_mul_f32 v[116:117], v[120:121], v[112:113] op_sel:[1,0]
	v_pk_mul_f32 v[118:119], v[120:121], v[114:115] op_sel:[1,0]
	v_pk_mul_f32 v[116:117], v[152:153], v[116:117]
	v_pk_mul_f32 v[118:119], v[154:155], v[118:119]
	v_cvt_pk_bf16_f32 v116, v116, v117
	s_nop 0
	v_cvt_pk_bf16_f32 v117, v118, v119
	global_store_dwordx4 v[168:169], v[112:115], off
	v_mov_b32_e32 v220, v116
	v_mov_b32_e32 v221, v117
	global_load_dwordx4 v[112:115], v[168:169], off offset:64
	s_waitcnt vmcnt(0)
	v_pk_fma_f32 v[108:109], v[140:141], v[108:109], v[112:113]
	v_pk_fma_f32 v[110:111], v[142:143], v[110:111], v[114:115]
	v_pk_mul_f32 v[112:113], v[120:121], v[108:109] op_sel:[1,0]
	v_pk_mul_f32 v[114:115], v[120:121], v[110:111] op_sel:[1,0]
	v_pk_mul_f32 v[112:113], v[156:157], v[112:113]
	v_pk_mul_f32 v[114:115], v[158:159], v[114:115]
	v_cvt_pk_bf16_f32 v112, v112, v113
	s_nop 0
	v_cvt_pk_bf16_f32 v113, v114, v115
	global_store_dwordx4 v[168:169], v[108:111], off offset:64
	v_mov_b32_e32 v222, v112
	v_mov_b32_e32 v223, v113
	v_lshl_add_u64 v[226:227], v[122:123], 0, v[224:225]
	s_nop 0
	v_permlane32_swap_b32_e32 v220, v222
	v_permlane32_swap_b32_e32 v221, v223
	s_nop 1
	v_permlane16_swap_b32_e32 v220, v222
	v_permlane16_swap_b32_e32 v221, v223
	global_store_dwordx4 v[226:227], v[220:223], off
	global_load_dwordx4 v[108:111], v[168:169], off offset:512
	s_waitcnt vmcnt(0)
	v_pk_fma_f32 v[104:105], v[136:137], v[104:105], v[108:109]
	v_pk_fma_f32 v[106:107], v[138:139], v[106:107], v[110:111]
	v_pk_mul_f32 v[108:109], v[120:121], v[104:105] op_sel:[1,0]
	v_pk_mul_f32 v[110:111], v[120:121], v[106:107] op_sel:[1,0]
	v_pk_mul_f32 v[108:109], v[148:149], v[108:109]
	v_pk_mul_f32 v[110:111], v[150:151], v[110:111]
	v_cvt_pk_bf16_f32 v108, v108, v109
	s_nop 0
	v_cvt_pk_bf16_f32 v109, v110, v111
	global_store_dwordx4 v[168:169], v[104:107], off offset:512
	v_mov_b32_e32 v220, v108
	v_mov_b32_e32 v221, v109
	global_load_dwordx4 v[104:107], v[168:169], off offset:576
	s_waitcnt vmcnt(0)
	v_pk_fma_f32 v[100:101], v[132:133], v[100:101], v[104:105]
	v_pk_fma_f32 v[102:103], v[134:135], v[102:103], v[106:107]
	v_pk_mul_f32 v[104:105], v[120:121], v[100:101] op_sel:[1,0]
	v_pk_mul_f32 v[106:107], v[120:121], v[102:103] op_sel:[1,0]
	v_pk_mul_f32 v[104:105], v[128:129], v[104:105]
	v_pk_mul_f32 v[106:107], v[130:131], v[106:107]
	v_cvt_pk_bf16_f32 v104, v104, v105
	s_nop 0
	v_cvt_pk_bf16_f32 v105, v106, v107
	global_store_dwordx4 v[168:169], v[100:103], off offset:576
	v_mov_b32_e32 v222, v104
	v_mov_b32_e32 v223, v105
	v_lshl_add_u64 v[226:227], v[122:123], 0, v[224:225]
	s_nop 0
	v_permlane32_swap_b32_e32 v220, v222
	v_permlane32_swap_b32_e32 v221, v223
	s_nop 1
	v_permlane16_swap_b32_e32 v220, v222
	v_permlane16_swap_b32_e32 v221, v223
	global_store_dwordx4 v[226:227], v[220:223], off offset:256
	global_load_dwordx4 v[100:103], v[172:173], off
	ds_read_b64 v[104:105], v33 offset:16640
	v_lshlrev_b64 v[106:107], 10, v[174:175]
	v_lshl_add_u64 v[106:107], v[106:107], 0, v[34:35]
	v_lshl_add_u64 v[106:107], v[106:107], 1, s[6:7]
	s_waitcnt lgkmcnt(0)
	v_pk_mul_f32 v[96:97], v[96:97], v[104:105] op_sel_hi:[1,0]
	v_pk_mul_f32 v[98:99], v[98:99], v[104:105] op_sel_hi:[1,0]
	v_pk_mul_f32 v[92:93], v[92:93], v[104:105] op_sel_hi:[1,0]
	v_pk_mul_f32 v[94:95], v[94:95], v[104:105] op_sel_hi:[1,0]
	v_pk_mul_f32 v[88:89], v[88:89], v[104:105] op_sel_hi:[1,0]
	v_pk_mul_f32 v[90:91], v[90:91], v[104:105] op_sel_hi:[1,0]
	v_pk_mul_f32 v[84:85], v[84:85], v[104:105] op_sel_hi:[1,0]
	v_pk_mul_f32 v[86:87], v[86:87], v[104:105] op_sel_hi:[1,0]
	s_waitcnt vmcnt(0)
	v_pk_fma_f32 v[96:97], v[144:145], v[96:97], v[100:101]
	v_pk_fma_f32 v[98:99], v[146:147], v[98:99], v[102:103]
	v_pk_mul_f32 v[100:101], v[104:105], v[96:97] op_sel:[1,0]
	v_pk_mul_f32 v[102:103], v[104:105], v[98:99] op_sel:[1,0]
	v_pk_mul_f32 v[100:101], v[152:153], v[100:101]
	v_pk_mul_f32 v[102:103], v[154:155], v[102:103]
	v_cvt_pk_bf16_f32 v100, v100, v101
	s_nop 0
	v_cvt_pk_bf16_f32 v101, v102, v103
	global_store_dwordx4 v[172:173], v[96:99], off
	v_mov_b32_e32 v220, v100
	v_mov_b32_e32 v221, v101
	global_load_dwordx4 v[96:99], v[172:173], off offset:64
	s_waitcnt vmcnt(0)
	v_pk_fma_f32 v[92:93], v[140:141], v[92:93], v[96:97]
	v_pk_fma_f32 v[94:95], v[142:143], v[94:95], v[98:99]
	v_pk_mul_f32 v[96:97], v[104:105], v[92:93] op_sel:[1,0]
	v_pk_mul_f32 v[98:99], v[104:105], v[94:95] op_sel:[1,0]
	v_pk_mul_f32 v[96:97], v[156:157], v[96:97]
	v_pk_mul_f32 v[98:99], v[158:159], v[98:99]
	v_cvt_pk_bf16_f32 v96, v96, v97
	s_nop 0
	v_cvt_pk_bf16_f32 v97, v98, v99
	global_store_dwordx4 v[172:173], v[92:95], off offset:64
	v_mov_b32_e32 v222, v96
	v_mov_b32_e32 v223, v97
	v_lshl_add_u64 v[226:227], v[106:107], 0, v[224:225]
	s_nop 0
	v_permlane32_swap_b32_e32 v220, v222
	v_permlane32_swap_b32_e32 v221, v223
	s_nop 1
	v_permlane16_swap_b32_e32 v220, v222
	v_permlane16_swap_b32_e32 v221, v223
	global_store_dwordx4 v[226:227], v[220:223], off
	global_load_dwordx4 v[92:95], v[172:173], off offset:512
	s_waitcnt vmcnt(0)
	v_pk_fma_f32 v[88:89], v[136:137], v[88:89], v[92:93]
	v_pk_fma_f32 v[90:91], v[138:139], v[90:91], v[94:95]
	v_pk_mul_f32 v[92:93], v[104:105], v[88:89] op_sel:[1,0]
	v_pk_mul_f32 v[94:95], v[104:105], v[90:91] op_sel:[1,0]
	v_pk_mul_f32 v[92:93], v[148:149], v[92:93]
	v_pk_mul_f32 v[94:95], v[150:151], v[94:95]
	v_cvt_pk_bf16_f32 v92, v92, v93
	s_nop 0
	v_cvt_pk_bf16_f32 v93, v94, v95
	global_store_dwordx4 v[172:173], v[88:91], off offset:512
	v_mov_b32_e32 v220, v92
	v_mov_b32_e32 v221, v93
	global_load_dwordx4 v[88:91], v[172:173], off offset:576
	s_waitcnt vmcnt(0)
; __device__ __forceinline__ unsigned cvt_pk_bf16(float lo, float hi) { unsigned r; asm volatile("v_cvt_pk_bf16_f32 %0, %1, %2" : "=v"(r) : "v"(lo), "v"(hi)); return r; }
;     __device__ __forceinline__ void fused(f32x4 (&acc)[2][2][4][2], const Unit& u, int wr, int wc, int fr, int fq, PG8_LAS unsigned char* lds, int wid, int lane) const {
;     ...
;             for (int m = 0; m < 4; ++m) { const int r = ai * HALF + wr * 64 + m * 16 + fr; const f32x2v sr = S[r]; const size_t off = (size_t)(u.pm * BM + r) * 1024 + col0;
; #pragma unroll
;                 for (int bj = 0; bj < 2; ++bj)
; #pragma unroll
;                     for (int n = 0; n < 2; ++n) { const f32x4 bs = *(const f32x4*)(base + off + bj * HALF + n * 16); const f32x4 x1 = bs + acc[ai][bj][m][n] * sr.x * gv[bj][n];
;                         const f32x4 o = x1 * sr.y * g2v[bj][n]; u32x2 w; w.x = cvt_pk_bf16(o[0], o[1]); w.y = cvt_pk_bf16(o[2], o[3]);
;                         if (!dry || x1[0] == 1.2345e38f) { *(f32x4*)(out + off + bj * HALF + n * 16) = x1; *(u32x2*)(xn + off + bj * HALF + n * 16) = w; } }
;                 if (m & 1) asm volatile("" ::: "memory"); }
	v_pk_fma_f32 v[84:85], v[132:133], v[84:85], v[88:89]
	v_pk_fma_f32 v[86:87], v[134:135], v[86:87], v[90:91]
	v_pk_mul_f32 v[88:89], v[104:105], v[84:85] op_sel:[1,0]
	v_pk_mul_f32 v[90:91], v[104:105], v[86:87] op_sel:[1,0]
	v_pk_mul_f32 v[88:89], v[128:129], v[88:89]
	v_pk_mul_f32 v[90:91], v[130:131], v[90:91]
	v_cvt_pk_bf16_f32 v88, v88, v89
	s_nop 0
	v_cvt_pk_bf16_f32 v89, v90, v91
	global_store_dwordx4 v[172:173], v[84:87], off offset:576
	v_mov_b32_e32 v222, v88
	v_mov_b32_e32 v223, v89
	v_lshl_add_u64 v[226:227], v[106:107], 0, v[224:225]
	s_nop 0
	v_permlane32_swap_b32_e32 v220, v222
	v_permlane32_swap_b32_e32 v221, v223
	s_nop 1
	v_permlane16_swap_b32_e32 v220, v222
	v_permlane16_swap_b32_e32 v221, v223
	global_store_dwordx4 v[226:227], v[220:223], off offset:256
	global_load_dwordx4 v[84:87], v[176:177], off
	ds_read_b64 v[88:89], v33 offset:16768
	v_lshlrev_b64 v[90:91], 10, v[178:179]
	v_lshl_add_u64 v[90:91], v[90:91], 0, v[34:35]
	v_lshl_add_u64 v[90:91], v[90:91], 1, s[6:7]
	s_waitcnt lgkmcnt(0)
	v_pk_mul_f32 v[80:81], v[80:81], v[88:89] op_sel_hi:[1,0]
	v_pk_mul_f32 v[82:83], v[82:83], v[88:89] op_sel_hi:[1,0]
	v_pk_mul_f32 v[76:77], v[76:77], v[88:89] op_sel_hi:[1,0]
	v_pk_mul_f32 v[78:79], v[78:79], v[88:89] op_sel_hi:[1,0]
	v_pk_mul_f32 v[72:73], v[72:73], v[88:89] op_sel_hi:[1,0]
	v_pk_mul_f32 v[74:75], v[74:75], v[88:89] op_sel_hi:[1,0]
	v_pk_mul_f32 v[68:69], v[68:69], v[88:89] op_sel_hi:[1,0]
	v_pk_mul_f32 v[70:71], v[70:71], v[88:89] op_sel_hi:[1,0]
	s_waitcnt vmcnt(0)
	v_pk_fma_f32 v[80:81], v[144:145], v[80:81], v[84:85]
	v_pk_fma_f32 v[82:83], v[146:147], v[82:83], v[86:87]
	v_pk_mul_f32 v[84:85], v[88:89], v[80:81] op_sel:[1,0]
	v_pk_mul_f32 v[86:87], v[88:89], v[82:83] op_sel:[1,0]
	v_pk_mul_f32 v[84:85], v[152:153], v[84:85]
	v_pk_mul_f32 v[86:87], v[154:155], v[86:87]
	v_cvt_pk_bf16_f32 v84, v84, v85
	s_nop 0
	v_cvt_pk_bf16_f32 v85, v86, v87
	global_store_dwordx4 v[176:177], v[80:83], off
	v_mov_b32_e32 v220, v84
	v_mov_b32_e32 v221, v85
	global_load_dwordx4 v[80:83], v[176:177], off offset:64
	s_waitcnt vmcnt(0)
	v_pk_fma_f32 v[76:77], v[140:141], v[76:77], v[80:81]
	v_pk_fma_f32 v[78:79], v[142:143], v[78:79], v[82:83]
	v_pk_mul_f32 v[80:81], v[88:89], v[76:77] op_sel:[1,0]
	v_pk_mul_f32 v[82:83], v[88:89], v[78:79] op_sel:[1,0]
	v_pk_mul_f32 v[80:81], v[156:157], v[80:81]
	v_pk_mul_f32 v[82:83], v[158:159], v[82:83]
	v_cvt_pk_bf16_f32 v80, v80, v81
	s_nop 0
	v_cvt_pk_bf16_f32 v81, v82, v83
	global_store_dwordx4 v[176:177], v[76:79], off offset:64
	v_mov_b32_e32 v222, v80
	v_mov_b32_e32 v223, v81
	v_lshl_add_u64 v[226:227], v[90:91], 0, v[224:225]
	s_nop 0
	v_permlane32_swap_b32_e32 v220, v222
	v_permlane32_swap_b32_e32 v221, v223
	s_nop 1
	v_permlane16_swap_b32_e32 v220, v222
	v_permlane16_swap_b32_e32 v221, v223
	global_store_dwordx4 v[226:227], v[220:223], off
	global_load_dwordx4 v[76:79], v[176:177], off offset:512
	s_waitcnt vmcnt(0)
	v_pk_fma_f32 v[72:73], v[136:137], v[72:73], v[76:77]
	v_pk_fma_f32 v[74:75], v[138:139], v[74:75], v[78:79]
	v_pk_mul_f32 v[76:77], v[88:89], v[72:73] op_sel:[1,0]
	v_pk_mul_f32 v[78:79], v[88:89], v[74:75] op_sel:[1,0]
	v_pk_mul_f32 v[76:77], v[148:149], v[76:77]
	v_pk_mul_f32 v[78:79], v[150:151], v[78:79]
	v_cvt_pk_bf16_f32 v76, v76, v77
	s_nop 0
	v_cvt_pk_bf16_f32 v77, v78, v79
	global_store_dwordx4 v[176:177], v[72:75], off offset:512
	v_mov_b32_e32 v220, v76
	v_mov_b32_e32 v221, v77
	global_load_dwordx4 v[72:75], v[176:177], off offset:576
	s_waitcnt vmcnt(0)
	v_pk_fma_f32 v[68:69], v[132:133], v[68:69], v[72:73]
	v_pk_fma_f32 v[70:71], v[134:135], v[70:71], v[74:75]
	v_pk_mul_f32 v[72:73], v[88:89], v[68:69] op_sel:[1,0]
	v_pk_mul_f32 v[74:75], v[88:89], v[70:71] op_sel:[1,0]
	v_pk_mul_f32 v[72:73], v[128:129], v[72:73]
	v_pk_mul_f32 v[74:75], v[130:131], v[74:75]
	v_cvt_pk_bf16_f32 v72, v72, v73
	s_nop 0
	v_cvt_pk_bf16_f32 v73, v74, v75
	global_store_dwordx4 v[176:177], v[68:71], off offset:576
	v_mov_b32_e32 v222, v72
	v_mov_b32_e32 v223, v73
	v_lshl_add_u64 v[226:227], v[90:91], 0, v[224:225]
	s_nop 0
	v_permlane32_swap_b32_e32 v220, v222
	v_permlane32_swap_b32_e32 v221, v223
	s_nop 1
	v_permlane16_swap_b32_e32 v220, v222
	v_permlane16_swap_b32_e32 v221, v223
	global_store_dwordx4 v[226:227], v[220:223], off offset:256
	global_load_dwordx4 v[68:71], v[180:181], off
	ds_read_b64 v[72:73], v33 offset:17408
	v_lshlrev_b64 v[74:75], 10, v[182:183]
	v_lshl_add_u64 v[74:75], v[74:75], 0, v[34:35]
	v_lshl_add_u64 v[74:75], v[74:75], 1, s[6:7]
	s_waitcnt lgkmcnt(0)
	v_pk_mul_f32 v[64:65], v[64:65], v[72:73] op_sel_hi:[1,0]
	v_pk_mul_f32 v[66:67], v[66:67], v[72:73] op_sel_hi:[1,0]
	v_pk_mul_f32 v[60:61], v[60:61], v[72:73] op_sel_hi:[1,0]
	v_pk_mul_f32 v[62:63], v[62:63], v[72:73] op_sel_hi:[1,0]
	v_pk_mul_f32 v[56:57], v[56:57], v[72:73] op_sel_hi:[1,0]
	v_pk_mul_f32 v[58:59], v[58:59], v[72:73] op_sel_hi:[1,0]
	v_pk_mul_f32 v[52:53], v[52:53], v[72:73] op_sel_hi:[1,0]
	v_pk_mul_f32 v[54:55], v[54:55], v[72:73] op_sel_hi:[1,0]
	s_waitcnt vmcnt(0)
	v_pk_fma_f32 v[64:65], v[144:145], v[64:65], v[68:69]
	v_pk_fma_f32 v[66:67], v[146:147], v[66:67], v[70:71]
	v_pk_mul_f32 v[68:69], v[72:73], v[64:65] op_sel:[1,0]
	v_pk_mul_f32 v[70:71], v[72:73], v[66:67] op_sel:[1,0]
	v_pk_mul_f32 v[68:69], v[152:153], v[68:69]
	v_pk_mul_f32 v[70:71], v[154:155], v[70:71]
	v_cvt_pk_bf16_f32 v68, v68, v69
	s_nop 0
	v_cvt_pk_bf16_f32 v69, v70, v71
	global_store_dwordx4 v[180:181], v[64:67], off
	v_mov_b32_e32 v220, v68
	v_mov_b32_e32 v221, v69
	global_load_dwordx4 v[64:67], v[180:181], off offset:64
	s_waitcnt vmcnt(0)
; __device__ __forceinline__ unsigned cvt_pk_bf16(float lo, float hi) { unsigned r; asm volatile("v_cvt_pk_bf16_f32 %0, %1, %2" : "=v"(r) : "v"(lo), "v"(hi)); return r; }
;     __device__ __forceinline__ void fused(f32x4 (&acc)[2][2][4][2], const Unit& u, int wr, int wc, int fr, int fq, PG8_LAS unsigned char* lds, int wid, int lane) const {
;     ...
;             for (int m = 0; m < 4; ++m) { const int r = ai * HALF + wr * 64 + m * 16 + fr; const f32x2v sr = S[r]; const size_t off = (size_t)(u.pm * BM + r) * 1024 + col0;
; #pragma unroll
;                 for (int bj = 0; bj < 2; ++bj)
; #pragma unroll
;                     for (int n = 0; n < 2; ++n) { const f32x4 bs = *(const f32x4*)(base + off + bj * HALF + n * 16); const f32x4 x1 = bs + acc[ai][bj][m][n] * sr.x * gv[bj][n];
;                         const f32x4 o = x1 * sr.y * g2v[bj][n]; u32x2 w; w.x = cvt_pk_bf16(o[0], o[1]); w.y = cvt_pk_bf16(o[2], o[3]);
;                         if (!dry || x1[0] == 1.2345e38f) { *(f32x4*)(out + off + bj * HALF + n * 16) = x1; *(u32x2*)(xn + off + bj * HALF + n * 16) = w; } }
;                 if (m & 1) asm volatile("" ::: "memory"); }
	v_pk_fma_f32 v[60:61], v[140:141], v[60:61], v[64:65]
	v_pk_fma_f32 v[62:63], v[142:143], v[62:63], v[66:67]
	v_pk_mul_f32 v[64:65], v[72:73], v[60:61] op_sel:[1,0]
	v_pk_mul_f32 v[66:67], v[72:73], v[62:63] op_sel:[1,0]
	v_pk_mul_f32 v[64:65], v[156:157], v[64:65]
	v_pk_mul_f32 v[66:67], v[158:159], v[66:67]
	v_cvt_pk_bf16_f32 v64, v64, v65
	s_nop 0
	v_cvt_pk_bf16_f32 v65, v66, v67
	global_store_dwordx4 v[180:181], v[60:63], off offset:64
	v_mov_b32_e32 v222, v64
	v_mov_b32_e32 v223, v65
	v_lshl_add_u64 v[226:227], v[74:75], 0, v[224:225]
	s_nop 0
	v_permlane32_swap_b32_e32 v220, v222
	v_permlane32_swap_b32_e32 v221, v223
	s_nop 1
	v_permlane16_swap_b32_e32 v220, v222
	v_permlane16_swap_b32_e32 v221, v223
	global_store_dwordx4 v[226:227], v[220:223], off
	global_load_dwordx4 v[60:63], v[180:181], off offset:512
	s_waitcnt vmcnt(0)
	v_pk_fma_f32 v[56:57], v[136:137], v[56:57], v[60:61]
	v_pk_fma_f32 v[58:59], v[138:139], v[58:59], v[62:63]
	v_pk_mul_f32 v[60:61], v[72:73], v[56:57] op_sel:[1,0]
	v_pk_mul_f32 v[62:63], v[72:73], v[58:59] op_sel:[1,0]
	v_pk_mul_f32 v[60:61], v[148:149], v[60:61]
	v_pk_mul_f32 v[62:63], v[150:151], v[62:63]
	v_cvt_pk_bf16_f32 v60, v60, v61
	s_nop 0
	v_cvt_pk_bf16_f32 v61, v62, v63
	global_store_dwordx4 v[180:181], v[56:59], off offset:512
	v_mov_b32_e32 v220, v60
	v_mov_b32_e32 v221, v61
	global_load_dwordx4 v[56:59], v[180:181], off offset:576
	s_waitcnt vmcnt(0)
	v_pk_fma_f32 v[52:53], v[132:133], v[52:53], v[56:57]
	v_pk_fma_f32 v[54:55], v[134:135], v[54:55], v[58:59]
	v_pk_mul_f32 v[56:57], v[72:73], v[52:53] op_sel:[1,0]
	v_pk_mul_f32 v[58:59], v[72:73], v[54:55] op_sel:[1,0]
	v_pk_mul_f32 v[56:57], v[128:129], v[56:57]
	v_pk_mul_f32 v[58:59], v[130:131], v[58:59]
	v_cvt_pk_bf16_f32 v56, v56, v57
	s_nop 0
	v_cvt_pk_bf16_f32 v57, v58, v59
	global_store_dwordx4 v[180:181], v[52:55], off offset:576
	v_mov_b32_e32 v222, v56
	v_mov_b32_e32 v223, v57
	v_lshl_add_u64 v[226:227], v[74:75], 0, v[224:225]
	s_nop 0
	v_permlane32_swap_b32_e32 v220, v222
	v_permlane32_swap_b32_e32 v221, v223
	s_nop 1
	v_permlane16_swap_b32_e32 v220, v222
	v_permlane16_swap_b32_e32 v221, v223
	global_store_dwordx4 v[226:227], v[220:223], off offset:256
	global_load_dwordx4 v[52:55], v[184:185], off
	ds_read_b64 v[56:57], v33 offset:17536
	v_lshlrev_b64 v[58:59], 10, v[186:187]
	v_lshl_add_u64 v[58:59], v[58:59], 0, v[34:35]
	v_lshl_add_u64 v[58:59], v[58:59], 1, s[6:7]
	s_waitcnt lgkmcnt(0)
	v_pk_mul_f32 v[48:49], v[48:49], v[56:57] op_sel_hi:[1,0]
	v_pk_mul_f32 v[50:51], v[50:51], v[56:57] op_sel_hi:[1,0]
	v_pk_mul_f32 v[44:45], v[44:45], v[56:57] op_sel_hi:[1,0]
	v_pk_mul_f32 v[46:47], v[46:47], v[56:57] op_sel_hi:[1,0]
	v_pk_mul_f32 v[40:41], v[40:41], v[56:57] op_sel_hi:[1,0]
	v_pk_mul_f32 v[42:43], v[42:43], v[56:57] op_sel_hi:[1,0]
	v_pk_mul_f32 v[36:37], v[36:37], v[56:57] op_sel_hi:[1,0]
	v_pk_mul_f32 v[38:39], v[38:39], v[56:57] op_sel_hi:[1,0]
	s_waitcnt vmcnt(0)
	v_pk_fma_f32 v[48:49], v[144:145], v[48:49], v[52:53]
	v_pk_fma_f32 v[50:51], v[146:147], v[50:51], v[54:55]
	v_pk_mul_f32 v[52:53], v[56:57], v[48:49] op_sel:[1,0]
	v_pk_mul_f32 v[54:55], v[56:57], v[50:51] op_sel:[1,0]
	v_pk_mul_f32 v[52:53], v[152:153], v[52:53]
	v_pk_mul_f32 v[54:55], v[154:155], v[54:55]
	v_cvt_pk_bf16_f32 v52, v52, v53
	s_nop 0
	v_cvt_pk_bf16_f32 v53, v54, v55
	global_store_dwordx4 v[184:185], v[48:51], off
	v_mov_b32_e32 v220, v52
	v_mov_b32_e32 v221, v53
	global_load_dwordx4 v[48:51], v[184:185], off offset:64
	s_waitcnt vmcnt(0)
	v_pk_fma_f32 v[44:45], v[140:141], v[44:45], v[48:49]
	v_pk_fma_f32 v[46:47], v[142:143], v[46:47], v[50:51]
	v_pk_mul_f32 v[48:49], v[56:57], v[44:45] op_sel:[1,0]
	v_pk_mul_f32 v[50:51], v[56:57], v[46:47] op_sel:[1,0]
	v_pk_mul_f32 v[48:49], v[156:157], v[48:49]
	v_pk_mul_f32 v[50:51], v[158:159], v[50:51]
	v_cvt_pk_bf16_f32 v48, v48, v49
	s_nop 0
	v_cvt_pk_bf16_f32 v49, v50, v51
	global_store_dwordx4 v[184:185], v[44:47], off offset:64
	v_mov_b32_e32 v222, v48
	v_mov_b32_e32 v223, v49
	v_lshl_add_u64 v[226:227], v[58:59], 0, v[224:225]
	s_nop 0
	v_permlane32_swap_b32_e32 v220, v222
	v_permlane32_swap_b32_e32 v221, v223
	s_nop 1
	v_permlane16_swap_b32_e32 v220, v222
	v_permlane16_swap_b32_e32 v221, v223
	global_store_dwordx4 v[226:227], v[220:223], off
	global_load_dwordx4 v[44:47], v[184:185], off offset:512
	s_waitcnt vmcnt(0)
	v_pk_fma_f32 v[40:41], v[136:137], v[40:41], v[44:45]
	v_pk_fma_f32 v[42:43], v[138:139], v[42:43], v[46:47]
	v_pk_mul_f32 v[44:45], v[56:57], v[40:41] op_sel:[1,0]
	v_pk_mul_f32 v[46:47], v[56:57], v[42:43] op_sel:[1,0]
	v_pk_mul_f32 v[44:45], v[148:149], v[44:45]
	v_pk_mul_f32 v[46:47], v[150:151], v[46:47]
	v_cvt_pk_bf16_f32 v44, v44, v45
	s_nop 0
	v_cvt_pk_bf16_f32 v45, v46, v47
	global_store_dwordx4 v[184:185], v[40:43], off offset:512
	v_mov_b32_e32 v220, v44
	v_mov_b32_e32 v221, v45
	global_load_dwordx4 v[40:43], v[184:185], off offset:576
	s_waitcnt vmcnt(0)
	v_pk_fma_f32 v[36:37], v[132:133], v[36:37], v[40:41]
	v_pk_fma_f32 v[38:39], v[134:135], v[38:39], v[42:43]
	v_pk_mul_f32 v[40:41], v[56:57], v[36:37] op_sel:[1,0]
	v_pk_mul_f32 v[42:43], v[56:57], v[38:39] op_sel:[1,0]
	v_pk_mul_f32 v[40:41], v[128:129], v[40:41]
	v_pk_mul_f32 v[42:43], v[130:131], v[42:43]
	v_cvt_pk_bf16_f32 v40, v40, v41
	s_nop 0
	v_cvt_pk_bf16_f32 v41, v42, v43
	global_store_dwordx4 v[184:185], v[36:39], off offset:576
	v_mov_b32_e32 v222, v40
	v_mov_b32_e32 v223, v41
	v_lshl_add_u64 v[226:227], v[58:59], 0, v[224:225]
	s_nop 0
	v_permlane32_swap_b32_e32 v220, v222
	v_permlane32_swap_b32_e32 v221, v223
	s_nop 1
	v_permlane16_swap_b32_e32 v220, v222
	v_permlane16_swap_b32_e32 v221, v223
	global_store_dwordx4 v[226:227], v[220:223], off offset:256
	global_load_dwordx4 v[36:39], v[188:189], off
	ds_read_b64 v[40:41], v33 offset:17664
	v_lshlrev_b64 v[42:43], 10, v[190:191]
	v_lshl_add_u64 v[42:43], v[42:43], 0, v[34:35]
	v_lshl_add_u64 v[42:43], v[42:43], 1, s[6:7]
	s_waitcnt lgkmcnt(0)
; __device__ __forceinline__ unsigned cvt_pk_bf16(float lo, float hi) { unsigned r; asm volatile("v_cvt_pk_bf16_f32 %0, %1, %2" : "=v"(r) : "v"(lo), "v"(hi)); return r; }
;     __device__ __forceinline__ void fused(f32x4 (&acc)[2][2][4][2], const Unit& u, int wr, int wc, int fr, int fq, PG8_LAS unsigned char* lds, int wid, int lane) const {
;     ...
;             for (int m = 0; m < 4; ++m) { const int r = ai * HALF + wr * 64 + m * 16 + fr; const f32x2v sr = S[r]; const size_t off = (size_t)(u.pm * BM + r) * 1024 + col0;
; #pragma unroll
;                 for (int bj = 0; bj < 2; ++bj)
; #pragma unroll
;                     for (int n = 0; n < 2; ++n) { const f32x4 bs = *(const f32x4*)(base + off + bj * HALF + n * 16); const f32x4 x1 = bs + acc[ai][bj][m][n] * sr.x * gv[bj][n];
;                         const f32x4 o = x1 * sr.y * g2v[bj][n]; u32x2 w; w.x = cvt_pk_bf16(o[0], o[1]); w.y = cvt_pk_bf16(o[2], o[3]);
;                         if (!dry || x1[0] == 1.2345e38f) { *(f32x4*)(out + off + bj * HALF + n * 16) = x1; *(u32x2*)(xn + off + bj * HALF + n * 16) = w; } }
;                 if (m & 1) asm volatile("" ::: "memory"); }
	v_pk_mul_f32 v[28:29], v[28:29], v[40:41] op_sel_hi:[1,0]
	v_pk_mul_f32 v[30:31], v[30:31], v[40:41] op_sel_hi:[1,0]
	v_pk_mul_f32 v[24:25], v[24:25], v[40:41] op_sel_hi:[1,0]
	v_pk_mul_f32 v[26:27], v[26:27], v[40:41] op_sel_hi:[1,0]
	v_pk_mul_f32 v[20:21], v[20:21], v[40:41] op_sel_hi:[1,0]
	v_pk_mul_f32 v[22:23], v[22:23], v[40:41] op_sel_hi:[1,0]
	v_pk_mul_f32 v[16:17], v[16:17], v[40:41] op_sel_hi:[1,0]
	v_pk_mul_f32 v[18:19], v[18:19], v[40:41] op_sel_hi:[1,0]
	s_waitcnt vmcnt(0)
	v_pk_fma_f32 v[28:29], v[144:145], v[28:29], v[36:37]
	v_pk_fma_f32 v[30:31], v[146:147], v[30:31], v[38:39]
	v_pk_mul_f32 v[36:37], v[40:41], v[28:29] op_sel:[1,0]
	v_pk_mul_f32 v[38:39], v[40:41], v[30:31] op_sel:[1,0]
	v_pk_mul_f32 v[36:37], v[152:153], v[36:37]
	v_pk_mul_f32 v[38:39], v[154:155], v[38:39]
	v_cvt_pk_bf16_f32 v36, v36, v37
	s_nop 0
	v_cvt_pk_bf16_f32 v37, v38, v39
	global_store_dwordx4 v[188:189], v[28:31], off
	v_mov_b32_e32 v220, v36
	v_mov_b32_e32 v221, v37
	global_load_dwordx4 v[28:31], v[188:189], off offset:64
	s_waitcnt vmcnt(0)
	v_pk_fma_f32 v[24:25], v[140:141], v[24:25], v[28:29]
	v_pk_fma_f32 v[26:27], v[142:143], v[26:27], v[30:31]
	v_pk_mul_f32 v[28:29], v[40:41], v[24:25] op_sel:[1,0]
	v_pk_mul_f32 v[30:31], v[40:41], v[26:27] op_sel:[1,0]
	v_pk_mul_f32 v[28:29], v[156:157], v[28:29]
	v_pk_mul_f32 v[30:31], v[158:159], v[30:31]
	v_cvt_pk_bf16_f32 v28, v28, v29
	s_nop 0
	v_cvt_pk_bf16_f32 v29, v30, v31
	global_store_dwordx4 v[188:189], v[24:27], off offset:64
	v_mov_b32_e32 v222, v28
	v_mov_b32_e32 v223, v29
	v_lshl_add_u64 v[226:227], v[42:43], 0, v[224:225]
	s_nop 0
	v_permlane32_swap_b32_e32 v220, v222
	v_permlane32_swap_b32_e32 v221, v223
	s_nop 1
	v_permlane16_swap_b32_e32 v220, v222
	v_permlane16_swap_b32_e32 v221, v223
	global_store_dwordx4 v[226:227], v[220:223], off
	global_load_dwordx4 v[24:27], v[188:189], off offset:512
	s_waitcnt vmcnt(0)
	v_pk_fma_f32 v[20:21], v[136:137], v[20:21], v[24:25]
	v_pk_fma_f32 v[22:23], v[138:139], v[22:23], v[26:27]
	v_pk_mul_f32 v[24:25], v[40:41], v[20:21] op_sel:[1,0]
	v_pk_mul_f32 v[26:27], v[40:41], v[22:23] op_sel:[1,0]
	v_pk_mul_f32 v[24:25], v[148:149], v[24:25]
	v_pk_mul_f32 v[26:27], v[150:151], v[26:27]
	v_cvt_pk_bf16_f32 v24, v24, v25
	s_nop 0
	v_cvt_pk_bf16_f32 v25, v26, v27
	global_store_dwordx4 v[188:189], v[20:23], off offset:512
	v_mov_b32_e32 v220, v24
	v_mov_b32_e32 v221, v25
	global_load_dwordx4 v[20:23], v[188:189], off offset:576
	s_waitcnt vmcnt(0)
	v_pk_fma_f32 v[16:17], v[132:133], v[16:17], v[20:21]
	v_pk_fma_f32 v[18:19], v[134:135], v[18:19], v[22:23]
	v_pk_mul_f32 v[20:21], v[40:41], v[16:17] op_sel:[1,0]
	v_pk_mul_f32 v[22:23], v[40:41], v[18:19] op_sel:[1,0]
	v_pk_mul_f32 v[20:21], v[128:129], v[20:21]
	v_pk_mul_f32 v[22:23], v[130:131], v[22:23]
	v_cvt_pk_bf16_f32 v20, v20, v21
	s_nop 0
	v_cvt_pk_bf16_f32 v21, v22, v23
	global_store_dwordx4 v[188:189], v[16:19], off offset:576
	v_mov_b32_e32 v222, v20
	v_mov_b32_e32 v223, v21
	v_lshl_add_u64 v[226:227], v[42:43], 0, v[224:225]
	s_nop 0
	v_permlane32_swap_b32_e32 v220, v222
	v_permlane32_swap_b32_e32 v221, v223
	s_nop 1
	v_permlane16_swap_b32_e32 v220, v222
	v_permlane16_swap_b32_e32 v221, v223
	global_store_dwordx4 v[226:227], v[220:223], off offset:256
	global_load_dwordx4 v[16:19], v[192:193], off
	ds_read_b64 v[20:21], v33 offset:17792
	v_lshlrev_b64 v[22:23], 10, v[204:205]
	v_lshl_add_u64 v[22:23], v[22:23], 0, v[34:35]
	v_lshl_add_u64 v[22:23], v[22:23], 1, s[6:7]
	s_waitcnt lgkmcnt(0)
	v_pk_mul_f32 v[12:13], v[12:13], v[20:21] op_sel_hi:[1,0]
	v_pk_mul_f32 v[14:15], v[14:15], v[20:21] op_sel_hi:[1,0]
	v_pk_mul_f32 v[8:9], v[8:9], v[20:21] op_sel_hi:[1,0]
	v_pk_mul_f32 v[10:11], v[10:11], v[20:21] op_sel_hi:[1,0]
	v_pk_mul_f32 v[4:5], v[4:5], v[20:21] op_sel_hi:[1,0]
	v_pk_mul_f32 v[6:7], v[6:7], v[20:21] op_sel_hi:[1,0]
	v_pk_mul_f32 v[0:1], v[0:1], v[20:21] op_sel_hi:[1,0]
	v_pk_mul_f32 v[2:3], v[2:3], v[20:21] op_sel_hi:[1,0]
	s_waitcnt vmcnt(0)
	v_pk_fma_f32 v[12:13], v[144:145], v[12:13], v[16:17]
	v_pk_fma_f32 v[14:15], v[146:147], v[14:15], v[18:19]
	v_pk_mul_f32 v[16:17], v[20:21], v[12:13] op_sel:[1,0]
	v_pk_mul_f32 v[18:19], v[20:21], v[14:15] op_sel:[1,0]
	v_pk_mul_f32 v[16:17], v[152:153], v[16:17]
	v_pk_mul_f32 v[18:19], v[154:155], v[18:19]
	v_cvt_pk_bf16_f32 v16, v16, v17
	s_nop 0
	v_cvt_pk_bf16_f32 v17, v18, v19
	global_store_dwordx4 v[192:193], v[12:15], off
	v_mov_b32_e32 v220, v16
	v_mov_b32_e32 v221, v17
	global_load_dwordx4 v[12:15], v[192:193], off offset:64
	s_waitcnt vmcnt(0)
	v_pk_fma_f32 v[8:9], v[140:141], v[8:9], v[12:13]
	v_pk_fma_f32 v[10:11], v[142:143], v[10:11], v[14:15]
	v_pk_mul_f32 v[12:13], v[20:21], v[8:9] op_sel:[1,0]
	v_pk_mul_f32 v[14:15], v[20:21], v[10:11] op_sel:[1,0]
	v_pk_mul_f32 v[12:13], v[156:157], v[12:13]
	v_pk_mul_f32 v[14:15], v[158:159], v[14:15]
	v_cvt_pk_bf16_f32 v12, v12, v13
	s_nop 0
	v_cvt_pk_bf16_f32 v13, v14, v15
	global_store_dwordx4 v[192:193], v[8:11], off offset:64
	v_mov_b32_e32 v222, v12
	v_mov_b32_e32 v223, v13
	v_lshl_add_u64 v[226:227], v[22:23], 0, v[224:225]
	s_nop 0
	v_permlane32_swap_b32_e32 v220, v222
	v_permlane32_swap_b32_e32 v221, v223
	s_nop 1
	v_permlane16_swap_b32_e32 v220, v222
	v_permlane16_swap_b32_e32 v221, v223
	global_store_dwordx4 v[226:227], v[220:223], off
	global_load_dwordx4 v[8:11], v[192:193], off offset:512
	s_waitcnt vmcnt(0)
	v_pk_fma_f32 v[4:5], v[136:137], v[4:5], v[8:9]
	v_pk_fma_f32 v[6:7], v[138:139], v[6:7], v[10:11]
	v_pk_mul_f32 v[8:9], v[20:21], v[4:5] op_sel:[1,0]
	v_pk_mul_f32 v[10:11], v[20:21], v[6:7] op_sel:[1,0]
	v_pk_mul_f32 v[8:9], v[148:149], v[8:9]
	v_pk_mul_f32 v[10:11], v[150:151], v[10:11]
	v_cvt_pk_bf16_f32 v8, v8, v9
	s_nop 0
	v_cvt_pk_bf16_f32 v9, v10, v11
	global_store_dwordx4 v[192:193], v[4:7], off offset:512
	v_mov_b32_e32 v220, v8
	v_mov_b32_e32 v221, v9
	global_load_dwordx4 v[4:7], v[192:193], off offset:576
	s_waitcnt vmcnt(0)
	v_pk_fma_f32 v[0:1], v[132:133], v[0:1], v[4:5]
	v_pk_fma_f32 v[2:3], v[134:135], v[2:3], v[6:7]
	v_pk_mul_f32 v[4:5], v[20:21], v[0:1] op_sel:[1,0]
	v_pk_mul_f32 v[6:7], v[20:21], v[2:3] op_sel:[1,0]
	v_pk_mul_f32 v[4:5], v[128:129], v[4:5]
	v_pk_mul_f32 v[6:7], v[130:131], v[6:7]
	v_cvt_pk_bf16_f32 v4, v4, v5
	s_nop 0
	v_cvt_pk_bf16_f32 v5, v6, v7
	global_store_dwordx4 v[192:193], v[0:3], off offset:576
	v_mov_b32_e32 v222, v4
	v_mov_b32_e32 v223, v5
	v_lshl_add_u64 v[226:227], v[22:23], 0, v[224:225]
	s_nop 0
	v_permlane32_swap_b32_e32 v220, v222
	v_permlane32_swap_b32_e32 v221, v223
	s_nop 1
	v_permlane16_swap_b32_e32 v220, v222
	v_permlane16_swap_b32_e32 v221, v223
	global_store_dwordx4 v[226:227], v[220:223], off offset:256
